# GEMM loops: post-MFMA barrier issued two MFMAs early with the tail MFMAs at priority 2, B0 reads rebalanced to L4/L8
# speedup vs baseline: 1.0386x; 1.0054x over previous
; #define PG8_STAGE(bufoff, gbase, voff) do { _Pragma("unroll") for (int _i = 0; _i < 2; ++_i) \
;     __builtin_amdgcn_global_load_lds((const unsigned*)((const char*)(gbase) + (voff)[_i]), (LAS unsigned*)(lds + (bufoff) + ldsw + _i * 8192), 16, 0, 0); } while (0)
; #define PG8_LDA(dst, b, h) do { _Pragma("unroll") for (int m = 0; m < 4; ++m) _Pragma("unroll") for (int k = 0; k < 2; ++k) dst[m][k] = *(const LAS bf16x8*)(lds + PG8_SA(b, h) + aoff + m * 2048 + k * 1024); } while (0)
; #define PG8_LDB(dst, b, h) do { _Pragma("unroll") for (int n = 0; n < 2; ++n) _Pragma("unroll") for (int k = 0; k < 2; ++k) dst[n][k] = *(const LAS bf16x8*)(lds + PG8_SB(b, h) + boff + n * 2048 + k * 1024); } while (0)
; #define PG8_MMA(ai, bj, At, Bt) do { __builtin_amdgcn_s_setprio(1); _Pragma("unroll") for (int m = 0; m < 4; ++m) _Pragma("unroll") for (int n = 0; n < 2; ++n) _Pragma("unroll") for (int k = 0; k < 2; ++k) \
;     acc[ai][bj][m][n] = __builtin_amdgcn_mfma_f32_16x16x32_bf16(Bt[n][k], At[m][k], acc[ai][bj][m][n], 0, 0, 0); __builtin_amdgcn_s_setprio(0); } while (0)
; #define PG8_WAIT_V(n) asm volatile("s_waitcnt vmcnt(" #n ")" ::: "memory")
; #define PG8_BAR __builtin_amdgcn_s_barrier()
; template <class Epi>
; DI void gemm_phase(LAS unsigned char* lds, const Gemm g, const Epi& E) {
;     ...
;     for (int t = 0; t < nt; t += 2) {
;       const bool last = (t == nt - 2);
;       const char* a1 = cA + (size_t)(t + 1) * kstep;
;       const char* a2 = last ? nA : cA + (size_t)(t + 2) * kstep; const char* b2 = last ? nB : cB + (size_t)(t + 2) * kstep;
;       const char* a3 = a2 + kstep; const char* b3 = b2 + kstep;
;       PG8_LDB(B0, 0, 0); PG8_SCHED; PG8_LDA(At, 0, 0); PG8_STAGE(PG8_SA(1, 1), a1 + hstepA, voffA);
;       PG8_WAIT_L(8); PG8_BAR; PG8_WAIT_L(0); PG8_MMA(0, 0, At, B0); PG8_BAR; PG8_SCHED;
;       PG8_LDB(B1, 0, 1); PG8_STAGE(PG8_SB(0, 0), b2, voffB);
;       PG8_BAR; PG8_WAIT_L(0); PG8_MMA(0, 1, At, B1); PG8_BAR;
;       PG8_LDA(At, 0, 1); PG8_STAGE(PG8_SA(0, 0), a2, voffA);
;       PG8_BAR; PG8_WAIT_L(0); PG8_MMA(1, 0, At, B0); PG8_BAR; PG8_SCHED;
;       PG8_STAGE(PG8_SB(0, 1), b2 + hstepB, voffB);
;       PG8_WAIT_V(6); PG8_BAR; PG8_MMA(1, 1, At, B1); PG8_BAR;
;       PG8_LDB(B0, 1, 0); PG8_SCHED; PG8_LDA(At, 1, 0); PG8_STAGE(PG8_SA(0, 1), a2 + hstepA, voffA);
;       PG8_WAIT_L(8); PG8_BAR; PG8_WAIT_L(0); PG8_MMA(0, 0, At, B0); PG8_BAR; PG8_SCHED;
.LBB0_190:
	s_add_u32 s36, s30, 0xfff80080
	s_addc_u32 s37, s31, -1
	s_add_i32 s60, 0, 0x10000
	s_cmp_eq_u32 s59, 28
	s_cselect_b32 s41, s13, s37
	s_cselect_b32 s40, s55, s36
	s_cselect_b32 s37, s3, s58
	s_cselect_b32 s36, s56, s57
	v_lshl_add_u64 v[162:163], s[30:31], 0, v[138:139]
	s_add_i32 m0, s27, 0xc000
	ds_read_b128 v[180:183], v145
	ds_read_b128 v[184:187], v145 offset:1024
	ds_read_b128 v[188:191], v145 offset:2048
	ds_read_b128 v[192:195], v145 offset:3072
	ds_read_b128 v[196:199], v145 offset:4096
	ds_read_b128 v[200:203], v145 offset:5120
	ds_read_b128 v[208:211], v145 offset:6144
	ds_read_b128 v[212:215], v145 offset:7168
	global_load_lds_dwordx4 v[162:163], off
	v_lshl_add_u64 v[162:163], s[30:31], 0, v[140:141]
	s_add_i32 m0, s27, 0xe000
	s_nop 0
	global_load_lds_dwordx4 v[162:163], off
	s_waitcnt lgkmcnt(8)
	s_barrier
	s_waitcnt lgkmcnt(0)
	s_setprio 1
	s_waitcnt lgkmcnt(0)
	v_mfma_f32_16x16x32_bf16 v[128:131], v[146:149], v[180:183], v[128:131]
	v_mfma_f32_16x16x32_bf16 v[120:123], v[154:157], v[180:183], v[120:123]
	v_mfma_f32_16x16x32_bf16 v[112:115], v[146:149], v[188:191], v[112:115]
	v_mfma_f32_16x16x32_bf16 v[104:107], v[154:157], v[188:191], v[104:107]
	v_mfma_f32_16x16x32_bf16 v[96:99], v[146:149], v[196:199], v[96:99]
	v_mfma_f32_16x16x32_bf16 v[88:91], v[154:157], v[196:199], v[88:91]
	v_mfma_f32_16x16x32_bf16 v[80:83], v[146:149], v[208:211], v[80:83]
	v_mfma_f32_16x16x32_bf16 v[72:75], v[154:157], v[208:211], v[72:75]
	v_mfma_f32_16x16x32_bf16 v[128:131], v[150:153], v[184:187], v[128:131]
	v_mfma_f32_16x16x32_bf16 v[120:123], v[158:161], v[184:187], v[120:123]
	v_mfma_f32_16x16x32_bf16 v[112:115], v[150:153], v[192:195], v[112:115]
	v_mfma_f32_16x16x32_bf16 v[104:107], v[158:161], v[192:195], v[104:107]
	v_mfma_f32_16x16x32_bf16 v[96:99], v[150:153], v[200:203], v[96:99]
	v_mfma_f32_16x16x32_bf16 v[88:91], v[158:161], v[200:203], v[88:91]
	s_setprio 2
	s_barrier
	v_mfma_f32_16x16x32_bf16 v[80:83], v[150:153], v[212:215], v[80:83]
	v_mfma_f32_16x16x32_bf16 v[72:75], v[158:161], v[212:215], v[72:75]
	s_setprio 0
	s_add_i32 s62, 0, 0x14000
	s_add_i32 s60, s60, s47
	ds_read_b128 v[216:219], v248 offset:16384
	ds_read_b128 v[220:223], v248 offset:17408
	ds_read_b128 v[224:227], v248 offset:18432
	ds_read_b128 v[228:231], v248 offset:19456
	v_lshl_add_u64 v[162:163], s[36:37], 0, v[2:3]
	s_mov_b32 m0, s60
	v_lshl_add_u64 v[232:233], s[36:37], 0, v[132:133]
	global_load_lds_dwordx4 v[162:163], off
	s_add_i32 m0, s60, 0x2000
	s_nop 0
	global_load_lds_dwordx4 v[232:233], off
	s_barrier
	s_waitcnt lgkmcnt(0)
	s_setprio 1
	s_waitcnt lgkmcnt(0)
	v_mfma_f32_16x16x32_bf16 v[124:127], v[216:219], v[180:183], v[124:127]
	v_mfma_f32_16x16x32_bf16 v[116:119], v[224:227], v[180:183], v[116:119]
	v_mfma_f32_16x16x32_bf16 v[108:111], v[216:219], v[188:191], v[108:111]
	v_mfma_f32_16x16x32_bf16 v[100:103], v[224:227], v[188:191], v[100:103]
	v_mfma_f32_16x16x32_bf16 v[92:95], v[216:219], v[196:199], v[92:95]
	v_mfma_f32_16x16x32_bf16 v[84:87], v[224:227], v[196:199], v[84:87]
	v_mfma_f32_16x16x32_bf16 v[76:79], v[216:219], v[208:211], v[76:79]
	v_mfma_f32_16x16x32_bf16 v[68:71], v[224:227], v[208:211], v[68:71]
	v_mfma_f32_16x16x32_bf16 v[124:127], v[220:223], v[184:187], v[124:127]
	v_mfma_f32_16x16x32_bf16 v[116:119], v[228:231], v[184:187], v[116:119]
	v_mfma_f32_16x16x32_bf16 v[108:111], v[220:223], v[192:195], v[108:111]
	v_mfma_f32_16x16x32_bf16 v[100:103], v[228:231], v[192:195], v[100:103]
	v_mfma_f32_16x16x32_bf16 v[92:95], v[220:223], v[200:203], v[92:95]
	v_mfma_f32_16x16x32_bf16 v[84:87], v[228:231], v[200:203], v[84:87]
	s_setprio 2
	s_barrier
	v_mfma_f32_16x16x32_bf16 v[76:79], v[220:223], v[212:215], v[76:79]
	v_mfma_f32_16x16x32_bf16 v[68:71], v[228:231], v[212:215], v[68:71]
	s_setprio 0
	s_mov_b32 m0, s27
	v_lshl_add_u64 v[234:235], s[40:41], 0, v[136:137]
	ds_read_b128 v[180:183], v145 offset:16384
	ds_read_b128 v[184:187], v145 offset:17408
	ds_read_b128 v[188:191], v145 offset:18432
	ds_read_b128 v[192:195], v145 offset:19456
	ds_read_b128 v[196:199], v145 offset:20480
	ds_read_b128 v[200:203], v145 offset:21504
	ds_read_b128 v[208:211], v145 offset:22528
	ds_read_b128 v[212:215], v145 offset:23552
	global_load_lds_dwordx4 v[234:235], off
	v_lshl_add_u64 v[236:237], s[40:41], 0, v[134:135]
	s_mov_b32 m0, s48
	s_nop 0
	global_load_lds_dwordx4 v[236:237], off
	s_waitcnt vmcnt(10)
	s_barrier
	s_waitcnt lgkmcnt(0)
	s_setprio 1
	s_waitcnt lgkmcnt(0)
	v_mfma_f32_16x16x32_bf16 v[64:67], v[146:149], v[180:183], v[64:67]
	v_mfma_f32_16x16x32_bf16 v[56:59], v[154:157], v[180:183], v[56:59]
	v_mfma_f32_16x16x32_bf16 v[48:51], v[146:149], v[188:191], v[48:51]
	v_mfma_f32_16x16x32_bf16 v[40:43], v[154:157], v[188:191], v[40:43]
	v_mfma_f32_16x16x32_bf16 v[32:35], v[146:149], v[196:199], v[32:35]
	v_mfma_f32_16x16x32_bf16 v[24:27], v[154:157], v[196:199], v[24:27]
	v_mfma_f32_16x16x32_bf16 v[16:19], v[146:149], v[208:211], v[16:19]
	v_mfma_f32_16x16x32_bf16 v[8:11], v[154:157], v[208:211], v[8:11]
	v_mfma_f32_16x16x32_bf16 v[64:67], v[150:153], v[184:187], v[64:67]
	v_mfma_f32_16x16x32_bf16 v[56:59], v[158:161], v[184:187], v[56:59]
	v_mfma_f32_16x16x32_bf16 v[48:51], v[150:153], v[192:195], v[48:51]
	v_mfma_f32_16x16x32_bf16 v[40:43], v[158:161], v[192:195], v[40:43]
	v_mfma_f32_16x16x32_bf16 v[32:35], v[150:153], v[200:203], v[32:35]
	v_mfma_f32_16x16x32_bf16 v[24:27], v[158:161], v[200:203], v[24:27]
	s_setprio 2
	s_barrier
; #define PG8_STAGE(bufoff, gbase, voff) do { _Pragma("unroll") for (int _i = 0; _i < 2; ++_i) \
;     __builtin_amdgcn_global_load_lds((const unsigned*)((const char*)(gbase) + (voff)[_i]), (LAS unsigned*)(lds + (bufoff) + ldsw + _i * 8192), 16, 0, 0); } while (0)
; #define PG8_LDA(dst, b, h) do { _Pragma("unroll") for (int m = 0; m < 4; ++m) _Pragma("unroll") for (int k = 0; k < 2; ++k) dst[m][k] = *(const LAS bf16x8*)(lds + PG8_SA(b, h) + aoff + m * 2048 + k * 1024); } while (0)
; #define PG8_LDB(dst, b, h) do { _Pragma("unroll") for (int n = 0; n < 2; ++n) _Pragma("unroll") for (int k = 0; k < 2; ++k) dst[n][k] = *(const LAS bf16x8*)(lds + PG8_SB(b, h) + boff + n * 2048 + k * 1024); } while (0)
; #define PG8_MMA(ai, bj, At, Bt) do { __builtin_amdgcn_s_setprio(1); _Pragma("unroll") for (int m = 0; m < 4; ++m) _Pragma("unroll") for (int n = 0; n < 2; ++n) _Pragma("unroll") for (int k = 0; k < 2; ++k) \
;     acc[ai][bj][m][n] = __builtin_amdgcn_mfma_f32_16x16x32_bf16(Bt[n][k], At[m][k], acc[ai][bj][m][n], 0, 0, 0); __builtin_amdgcn_s_setprio(0); } while (0)
; #define PG8_WAIT_V(n) asm volatile("s_waitcnt vmcnt(" #n ")" ::: "memory")
; #define PG8_WAIT_L(n) asm volatile("s_waitcnt lgkmcnt(" #n ")" ::: "memory")
; #define PG8_BAR __builtin_amdgcn_s_barrier()
; #define PG8_SCHED __builtin_amdgcn_sched_barrier(0)
; template <class Epi>
; DI void gemm_phase(LAS unsigned char* lds, const Gemm g, const Epi& E) {
;     ...
;       PG8_WAIT_V(6); PG8_BAR; PG8_MMA(1, 1, At, B1); PG8_BAR;
;       PG8_LDB(B0, 1, 0); PG8_SCHED; PG8_LDA(At, 1, 0); PG8_STAGE(PG8_SA(0, 1), a2 + hstepA, voffA);
;       PG8_WAIT_L(8); PG8_BAR; PG8_WAIT_L(0); PG8_MMA(0, 0, At, B0); PG8_BAR; PG8_SCHED;
;       PG8_LDB(B1, 1, 1); PG8_STAGE(PG8_SB(1, 0), b3, voffB);
;       PG8_BAR; PG8_WAIT_L(0); PG8_MMA(0, 1, At, B1); PG8_BAR;
;       PG8_LDA(At, 1, 1); PG8_STAGE(PG8_SA(1, 0), a3, voffA);
;       PG8_BAR; PG8_WAIT_L(0); PG8_MMA(1, 0, At, B0); PG8_BAR; PG8_SCHED;
	v_mfma_f32_16x16x32_bf16 v[16:19], v[150:153], v[212:215], v[16:19]
	v_mfma_f32_16x16x32_bf16 v[8:11], v[158:161], v[212:215], v[8:11]
	s_setprio 0
	ds_read_b128 v[146:149], v248 offset:32768
	ds_read_b128 v[150:153], v248 offset:33792
	ds_read_b128 v[154:157], v248 offset:34816
	ds_read_b128 v[158:161], v248 offset:35840
	s_add_u32 s60, s36, 0x80000
	s_addc_u32 s61, s37, 0
	s_add_i32 s62, s62, s47
	v_lshl_add_u64 v[246:247], s[60:61], 0, v[2:3]
	s_mov_b32 m0, s62
	s_nop 0
	global_load_lds_dwordx4 v[246:247], off
	v_lshl_add_u64 v[246:247], s[60:61], 0, v[132:133]
	s_add_i32 m0, s62, 0x2000
	s_nop 0
	global_load_lds_dwordx4 v[246:247], off
	s_waitcnt vmcnt(6)
	s_barrier
	s_setprio 1
	v_mfma_f32_16x16x32_bf16 v[60:63], v[216:219], v[180:183], v[60:63]
	v_mfma_f32_16x16x32_bf16 v[52:55], v[224:227], v[180:183], v[52:55]
	v_mfma_f32_16x16x32_bf16 v[44:47], v[216:219], v[188:191], v[44:47]
	v_mfma_f32_16x16x32_bf16 v[36:39], v[224:227], v[188:191], v[36:39]
	v_mfma_f32_16x16x32_bf16 v[28:31], v[216:219], v[196:199], v[28:31]
	v_mfma_f32_16x16x32_bf16 v[20:23], v[224:227], v[196:199], v[20:23]
	v_mfma_f32_16x16x32_bf16 v[12:15], v[216:219], v[208:211], v[12:15]
	v_mfma_f32_16x16x32_bf16 v[4:7], v[224:227], v[208:211], v[4:7]
	v_mfma_f32_16x16x32_bf16 v[60:63], v[220:223], v[184:187], v[60:63]
	v_mfma_f32_16x16x32_bf16 v[52:55], v[228:231], v[184:187], v[52:55]
	v_mfma_f32_16x16x32_bf16 v[44:47], v[220:223], v[192:195], v[44:47]
	v_mfma_f32_16x16x32_bf16 v[36:39], v[228:231], v[192:195], v[36:39]
	v_mfma_f32_16x16x32_bf16 v[28:31], v[220:223], v[200:203], v[28:31]
	v_mfma_f32_16x16x32_bf16 v[20:23], v[228:231], v[200:203], v[20:23]
	s_setprio 2
	s_barrier
	v_mfma_f32_16x16x32_bf16 v[12:15], v[220:223], v[212:215], v[12:15]
	v_mfma_f32_16x16x32_bf16 v[4:7], v[228:231], v[212:215], v[4:7]
	s_setprio 0
	s_add_i32 s60, 0, 0x18000
	s_add_u32 s40, s40, 0x80000
	s_addc_u32 s41, s41, 0
	s_mov_b32 m0, s49
	v_lshl_add_u64 v[216:217], s[40:41], 0, v[136:137]
	ds_read_b128 v[180:183], v145 offset:32768
	ds_read_b128 v[184:187], v145 offset:33792
	ds_read_b128 v[188:191], v145 offset:34816
	ds_read_b128 v[192:195], v145 offset:35840
	ds_read_b128 v[196:199], v145 offset:36864
	ds_read_b128 v[200:203], v145 offset:37888
	ds_read_b128 v[208:211], v145 offset:38912
	ds_read_b128 v[212:215], v145 offset:39936
	global_load_lds_dwordx4 v[216:217], off
	v_lshl_add_u64 v[216:217], s[40:41], 0, v[134:135]
	s_mov_b32 m0, s50
	s_nop 0
	global_load_lds_dwordx4 v[216:217], off
	s_waitcnt lgkmcnt(8)
	s_barrier
	s_waitcnt lgkmcnt(0)
	s_setprio 1
	s_waitcnt lgkmcnt(0)
	v_mfma_f32_16x16x32_bf16 v[128:131], v[146:149], v[180:183], v[128:131]
	v_mfma_f32_16x16x32_bf16 v[120:123], v[154:157], v[180:183], v[120:123]
	v_mfma_f32_16x16x32_bf16 v[112:115], v[146:149], v[188:191], v[112:115]
	v_mfma_f32_16x16x32_bf16 v[104:107], v[154:157], v[188:191], v[104:107]
	v_mfma_f32_16x16x32_bf16 v[96:99], v[146:149], v[196:199], v[96:99]
	v_mfma_f32_16x16x32_bf16 v[88:91], v[154:157], v[196:199], v[88:91]
	v_mfma_f32_16x16x32_bf16 v[80:83], v[146:149], v[208:211], v[80:83]
	v_mfma_f32_16x16x32_bf16 v[72:75], v[154:157], v[208:211], v[72:75]
	v_mfma_f32_16x16x32_bf16 v[128:131], v[150:153], v[184:187], v[128:131]
	v_mfma_f32_16x16x32_bf16 v[120:123], v[158:161], v[184:187], v[120:123]
	v_mfma_f32_16x16x32_bf16 v[112:115], v[150:153], v[192:195], v[112:115]
	v_mfma_f32_16x16x32_bf16 v[104:107], v[158:161], v[192:195], v[104:107]
	v_mfma_f32_16x16x32_bf16 v[96:99], v[150:153], v[200:203], v[96:99]
	v_mfma_f32_16x16x32_bf16 v[88:91], v[158:161], v[200:203], v[88:91]
	s_setprio 2
	s_barrier
	v_mfma_f32_16x16x32_bf16 v[80:83], v[150:153], v[212:215], v[80:83]
	v_mfma_f32_16x16x32_bf16 v[72:75], v[158:161], v[212:215], v[72:75]
	s_setprio 0
	s_add_i32 s40, 0, 0x1c000
	s_add_i32 s41, s60, s47
	v_lshl_add_u64 v[162:163], v[162:163], 0, s[84:85]
	s_mov_b32 m0, s41
	ds_read_b128 v[216:219], v248 offset:49152
	ds_read_b128 v[220:223], v248 offset:50176
	ds_read_b128 v[224:227], v248 offset:51200
	ds_read_b128 v[228:231], v248 offset:52224
	global_load_lds_dwordx4 v[162:163], off
	v_lshl_add_u64 v[162:163], v[232:233], 0, s[84:85]
	s_add_i32 m0, s41, 0x2000
	s_nop 0
	global_load_lds_dwordx4 v[162:163], off
	s_barrier
	s_waitcnt lgkmcnt(0)
	s_setprio 1
	s_waitcnt lgkmcnt(0)
	v_mfma_f32_16x16x32_bf16 v[124:127], v[216:219], v[180:183], v[124:127]
	v_mfma_f32_16x16x32_bf16 v[116:119], v[224:227], v[180:183], v[116:119]
	v_mfma_f32_16x16x32_bf16 v[108:111], v[216:219], v[188:191], v[108:111]
	v_mfma_f32_16x16x32_bf16 v[100:103], v[224:227], v[188:191], v[100:103]
	v_mfma_f32_16x16x32_bf16 v[92:95], v[216:219], v[196:199], v[92:95]
	v_mfma_f32_16x16x32_bf16 v[84:87], v[224:227], v[196:199], v[84:87]
	v_mfma_f32_16x16x32_bf16 v[76:79], v[216:219], v[208:211], v[76:79]
	v_mfma_f32_16x16x32_bf16 v[68:71], v[224:227], v[208:211], v[68:71]
	v_mfma_f32_16x16x32_bf16 v[124:127], v[220:223], v[184:187], v[124:127]
	v_mfma_f32_16x16x32_bf16 v[116:119], v[228:231], v[184:187], v[116:119]
	v_mfma_f32_16x16x32_bf16 v[108:111], v[220:223], v[192:195], v[108:111]
	v_mfma_f32_16x16x32_bf16 v[100:103], v[228:231], v[192:195], v[100:103]
	v_mfma_f32_16x16x32_bf16 v[92:95], v[220:223], v[200:203], v[92:95]
	v_mfma_f32_16x16x32_bf16 v[84:87], v[228:231], v[200:203], v[84:87]
	s_setprio 2
	s_barrier
; DI unsigned cvt_pk_bf16(float lo, float hi) { const f32x2 v = {lo, hi}; const bf16x2_t r = __builtin_convertvector(v, bf16x2_t); return __builtin_bit_cast(unsigned, r); }
; #define PG8_STAGE(bufoff, gbase, voff) do { _Pragma("unroll") for (int _i = 0; _i < 2; ++_i) \
;     __builtin_amdgcn_global_load_lds((const unsigned*)((const char*)(gbase) + (voff)[_i]), (LAS unsigned*)(lds + (bufoff) + ldsw + _i * 8192), 16, 0, 0); } while (0)
; #define PG8_MMA(ai, bj, At, Bt) do { __builtin_amdgcn_s_setprio(1); _Pragma("unroll") for (int m = 0; m < 4; ++m) _Pragma("unroll") for (int n = 0; n < 2; ++n) _Pragma("unroll") for (int k = 0; k < 2; ++k) \
;     acc[ai][bj][m][n] = __builtin_amdgcn_mfma_f32_16x16x32_bf16(Bt[n][k], At[m][k], acc[ai][bj][m][n], 0, 0, 0); __builtin_amdgcn_s_setprio(0); } while (0)
; #define PG8_WAIT_V(n) asm volatile("s_waitcnt vmcnt(" #n ")" ::: "memory")
; #define PG8_WAIT_L(n) asm volatile("s_waitcnt lgkmcnt(" #n ")" ::: "memory")
; #define PG8_BAR __builtin_amdgcn_s_barrier()
; #define PG8_SCHED __builtin_amdgcn_sched_barrier(0)
; DI float silu_f(float g) { return g * __builtin_amdgcn_rcpf(1.0f + __expf(-g)); }
; template <class Epi>
; DI void gemm_phase(LAS unsigned char* lds, const Gemm g, const Epi& E) {
;     ...
;       PG8_BAR; PG8_WAIT_L(0); PG8_MMA(1, 0, At, B0); PG8_BAR; PG8_SCHED;
;       PG8_STAGE(PG8_SB(1, 1), b3 + hstepB, voffB);
;       PG8_WAIT_V(6); PG8_BAR; PG8_MMA(1, 1, At, B1); PG8_BAR;
;   DI void operator()(const f32x4 (&acc)[2][2][4][2], const Unit& u, int wr, int wc, int fr, int fq) const {
;     const int row0 = u.pm * BM + wr * 64 + fr, col0 = u.pn * HALF + wc * 32 + 8 * fq;
; #pragma unroll
;     for (int ai = 0; ai < 2; ++ai)
; #pragma unroll
;       for (int m = 0; m < 4; ++m) {
;         const f32x4 g0 = acc[ai][0][m][0], g1 = acc[ai][0][m][1], u0 = acc[ai][1][m][0], u1 = acc[ai][1][m][1];
;         u32x4 w;
;         w.x = cvt_pk_bf16(silu_f(g0[0]) * u0[0], silu_f(g0[1]) * u0[1]); w.y = cvt_pk_bf16(silu_f(g0[2]) * u0[2], silu_f(g0[3]) * u0[3]);
;         w.z = cvt_pk_bf16(silu_f(g1[0]) * u1[0], silu_f(g1[1]) * u1[1]); w.w = cvt_pk_bf16(silu_f(g1[2]) * u1[2], silu_f(g1[3]) * u1[3]);
;         *(u32x4*)(H + (size_t)(row0 + ai * HALF + m * 16) * DFF + col0) = w;
	v_mfma_f32_16x16x32_bf16 v[76:79], v[220:223], v[212:215], v[76:79]
	v_mfma_f32_16x16x32_bf16 v[68:71], v[228:231], v[212:215], v[68:71]
	s_setprio 0
	s_mov_b32 m0, s51
	v_lshl_add_u64 v[162:163], v[234:235], 0, s[84:85]
	ds_read_b128 v[180:183], v145 offset:49152
	ds_read_b128 v[184:187], v145 offset:50176
	ds_read_b128 v[188:191], v145 offset:51200
	ds_read_b128 v[192:195], v145 offset:52224
	ds_read_b128 v[196:199], v145 offset:53248
	ds_read_b128 v[200:203], v145 offset:54272
	ds_read_b128 v[208:211], v145 offset:55296
	ds_read_b128 v[212:215], v145 offset:56320
	global_load_lds_dwordx4 v[162:163], off
	v_lshl_add_u64 v[162:163], v[236:237], 0, s[84:85]
	s_mov_b32 m0, s52
	s_nop 0
	global_load_lds_dwordx4 v[162:163], off
	s_waitcnt vmcnt(10)
	s_barrier
	s_waitcnt lgkmcnt(0)
	s_setprio 1
	s_waitcnt lgkmcnt(0)
	v_mfma_f32_16x16x32_bf16 v[64:67], v[146:149], v[180:183], v[64:67]
	v_mfma_f32_16x16x32_bf16 v[56:59], v[154:157], v[180:183], v[56:59]
	v_mfma_f32_16x16x32_bf16 v[48:51], v[146:149], v[188:191], v[48:51]
	v_mfma_f32_16x16x32_bf16 v[40:43], v[154:157], v[188:191], v[40:43]
	v_mfma_f32_16x16x32_bf16 v[32:35], v[146:149], v[196:199], v[32:35]
	v_mfma_f32_16x16x32_bf16 v[24:27], v[154:157], v[196:199], v[24:27]
	v_mfma_f32_16x16x32_bf16 v[16:19], v[146:149], v[208:211], v[16:19]
	v_mfma_f32_16x16x32_bf16 v[8:11], v[154:157], v[208:211], v[8:11]
	v_mfma_f32_16x16x32_bf16 v[64:67], v[150:153], v[184:187], v[64:67]
	v_mfma_f32_16x16x32_bf16 v[56:59], v[158:161], v[184:187], v[56:59]
	v_mfma_f32_16x16x32_bf16 v[48:51], v[150:153], v[192:195], v[48:51]
	v_mfma_f32_16x16x32_bf16 v[40:43], v[158:161], v[192:195], v[40:43]
	v_mfma_f32_16x16x32_bf16 v[32:35], v[150:153], v[200:203], v[32:35]
	v_mfma_f32_16x16x32_bf16 v[24:27], v[158:161], v[200:203], v[24:27]
	s_setprio 2
	s_barrier
	v_mfma_f32_16x16x32_bf16 v[16:19], v[150:153], v[212:215], v[16:19]
	v_mfma_f32_16x16x32_bf16 v[8:11], v[158:161], v[212:215], v[8:11]
	s_setprio 0
	ds_read_b128 v[146:149], v248
	ds_read_b128 v[150:153], v248 offset:1024
	ds_read_b128 v[154:157], v248 offset:2048
	ds_read_b128 v[158:161], v248 offset:3072
	s_add_u32 s36, s36, 0x80080
	s_addc_u32 s37, s37, 0
	s_add_i32 s40, s40, s47
	v_lshl_add_u64 v[246:247], s[36:37], 0, v[2:3]
	s_mov_b32 m0, s40
	s_nop 0
	global_load_lds_dwordx4 v[246:247], off
	v_lshl_add_u64 v[246:247], s[36:37], 0, v[132:133]
	s_add_i32 m0, s40, 0x2000
	s_nop 0
	global_load_lds_dwordx4 v[246:247], off
	s_waitcnt vmcnt(6)
	s_barrier
	s_setprio 1
	v_mfma_f32_16x16x32_bf16 v[60:63], v[216:219], v[180:183], v[60:63]
	v_mfma_f32_16x16x32_bf16 v[52:55], v[224:227], v[180:183], v[52:55]
	v_mfma_f32_16x16x32_bf16 v[44:47], v[216:219], v[188:191], v[44:47]
	v_mfma_f32_16x16x32_bf16 v[36:39], v[224:227], v[188:191], v[36:39]
	v_mfma_f32_16x16x32_bf16 v[28:31], v[216:219], v[196:199], v[28:31]
	v_mfma_f32_16x16x32_bf16 v[20:23], v[224:227], v[196:199], v[20:23]
	v_mfma_f32_16x16x32_bf16 v[12:15], v[216:219], v[208:211], v[12:15]
	v_mfma_f32_16x16x32_bf16 v[4:7], v[224:227], v[208:211], v[4:7]
	v_mfma_f32_16x16x32_bf16 v[60:63], v[220:223], v[184:187], v[60:63]
	v_mfma_f32_16x16x32_bf16 v[52:55], v[228:231], v[184:187], v[52:55]
	v_mfma_f32_16x16x32_bf16 v[44:47], v[220:223], v[192:195], v[44:47]
	v_mfma_f32_16x16x32_bf16 v[36:39], v[228:231], v[192:195], v[36:39]
	v_mfma_f32_16x16x32_bf16 v[28:31], v[220:223], v[200:203], v[28:31]
	v_mfma_f32_16x16x32_bf16 v[20:23], v[228:231], v[200:203], v[20:23]
	s_setprio 2
	s_barrier
	v_mfma_f32_16x16x32_bf16 v[12:15], v[220:223], v[212:215], v[12:15]
	v_mfma_f32_16x16x32_bf16 v[4:7], v[228:231], v[212:215], v[4:7]
	s_setprio 0
	s_add_i32 s59, s59, 2
	s_add_u32 s30, s30, 0x100
	s_addc_u32 s31, s31, 0
	s_add_u32 s57, s57, 0x100
	s_addc_u32 s58, s58, 0
	s_cmp_gt_u32 s59, 29
	s_cbranch_scc0 .LBB0_190
	s_waitcnt lgkmcnt(0)
	v_mul_f32_e32 v147, 0xbfb8aa3b, v128
	v_exp_f32_e32 v147, v147
	v_lshl_or_b32 v148, s54, 7, v144
	v_lshl_add_u32 v146, s26, 8, v142
	v_ashrrev_i32_e32 v149, 31, v148
	v_add_f32_e32 v147, 1.0, v147
	v_rcp_f32_e32 v150, v147
	v_mul_f32_e32 v147, 0xbfb8aa3b, v129
	v_exp_f32_e32 v147, v147
	s_movk_i32 s3, 0x2c00
	s_movk_i32 s5, 0x2c00
	s_and_b64 vcc, exec, s[38:39]
	v_add_f32_e32 v147, 1.0, v147
	v_rcp_f32_e32 v151, v147
	s_mov_b32 s54, s2
	s_mov_b32 s26, s12
	s_mov_b64 s[36:37], s[22:23]
	v_pk_mul_f32 v[128:129], v[128:129], v[150:151]
	s_nop 0
	v_pk_mul_f32 v[124:125], v[128:129], v[124:125]
	s_nop 0
	v_cvt_pk_bf16_f32 v124, v124, v125
	v_mul_f32_e32 v125, 0xbfb8aa3b, v130
	v_exp_f32_e32 v125, v125
	s_nop 0
	v_add_f32_e32 v125, 1.0, v125
	v_rcp_f32_e32 v128, v125
	v_mul_f32_e32 v125, 0xbfb8aa3b, v131
	v_exp_f32_e32 v125, v125
	s_nop 0
	v_add_f32_e32 v125, 1.0, v125
	v_rcp_f32_e32 v129, v125
	s_nop 0
	v_pk_mul_f32 v[128:129], v[130:131], v[128:129]
	s_nop 0
	v_pk_mul_f32 v[126:127], v[128:129], v[126:127]
	s_nop 0
	v_cvt_pk_bf16_f32 v125, v126, v127
	v_mul_f32_e32 v126, 0xbfb8aa3b, v120
	v_mul_f32_e32 v127, 0xbfb8aa3b, v121
	v_exp_f32_e32 v126, v126
	v_exp_f32_e32 v127, v127
	v_add_f32_e32 v126, 1.0, v126
	v_add_f32_e32 v127, 1.0, v127
	v_rcp_f32_e32 v126, v126
	v_rcp_f32_e32 v127, v127
	s_nop 0
	v_pk_mul_f32 v[120:121], v[120:121], v[126:127]
	s_nop 0
	v_pk_mul_f32 v[116:117], v[120:121], v[116:117]
	s_nop 0
	v_cvt_pk_bf16_f32 v126, v116, v117
	v_mul_f32_e32 v116, 0xbfb8aa3b, v122
	v_mul_f32_e32 v117, 0xbfb8aa3b, v123
	v_exp_f32_e32 v116, v116
	v_exp_f32_e32 v117, v117
	v_add_f32_e32 v116, 1.0, v116
	v_add_f32_e32 v117, 1.0, v117
	v_rcp_f32_e32 v116, v116
	v_rcp_f32_e32 v117, v117
	s_nop 0
	v_pk_mul_f32 v[116:117], v[122:123], v[116:117]
	s_nop 0
	v_pk_mul_f32 v[116:117], v[116:117], v[118:119]
; DI unsigned cvt_pk_bf16(float lo, float hi) { const f32x2 v = {lo, hi}; const bf16x2_t r = __builtin_convertvector(v, bf16x2_t); return __builtin_bit_cast(unsigned, r); }
; DI float silu_f(float g) { return g * __builtin_amdgcn_rcpf(1.0f + __expf(-g)); }
;   DI void operator()(const f32x4 (&acc)[2][2][4][2], const Unit& u, int wr, int wc, int fr, int fq) const {
;     ...
;     for (int ai = 0; ai < 2; ++ai)
; #pragma unroll
;       for (int m = 0; m < 4; ++m) {
;         const f32x4 g0 = acc[ai][0][m][0], g1 = acc[ai][0][m][1], u0 = acc[ai][1][m][0], u1 = acc[ai][1][m][1];
;         u32x4 w;
;         w.x = cvt_pk_bf16(silu_f(g0[0]) * u0[0], silu_f(g0[1]) * u0[1]); w.y = cvt_pk_bf16(silu_f(g0[2]) * u0[2], silu_f(g0[3]) * u0[3]);
;         w.z = cvt_pk_bf16(silu_f(g1[0]) * u1[0], silu_f(g1[1]) * u1[1]); w.w = cvt_pk_bf16(silu_f(g1[2]) * u1[2], silu_f(g1[3]) * u1[3]);
;         *(u32x4*)(H + (size_t)(row0 + ai * HALF + m * 16) * DFF + col0) = w;
;       }
	v_lshlrev_b64 v[118:119], 1, v[148:149]
	v_cvt_pk_bf16_f32 v127, v116, v117
	v_mov_b64_e32 v[116:117], s[0:1]
	v_mad_i64_i32 v[120:121], s[30:31], v146, s3, v[116:117]
	v_lshl_add_u64 v[120:121], v[120:121], 0, v[118:119]
	global_store_dwordx4 v[120:121], v[124:127], off
	v_mul_f32_e32 v120, 0xbfb8aa3b, v112
	v_mul_f32_e32 v121, 0xbfb8aa3b, v113
	v_exp_f32_e32 v120, v120
	v_exp_f32_e32 v121, v121
	v_add_f32_e32 v120, 1.0, v120
	v_add_f32_e32 v121, 1.0, v121
	v_rcp_f32_e32 v120, v120
	v_rcp_f32_e32 v121, v121
	s_nop 0
	v_pk_mul_f32 v[112:113], v[112:113], v[120:121]
	s_nop 0
	v_pk_mul_f32 v[108:109], v[112:113], v[108:109]
	s_nop 0
	v_cvt_pk_bf16_f32 v108, v108, v109
	v_mul_f32_e32 v109, 0xbfb8aa3b, v114
	v_exp_f32_e32 v109, v109
	s_nop 0
	v_add_f32_e32 v109, 1.0, v109
	v_rcp_f32_e32 v112, v109
	v_mul_f32_e32 v109, 0xbfb8aa3b, v115
	v_exp_f32_e32 v109, v109
	s_nop 0
	v_add_f32_e32 v109, 1.0, v109
	v_rcp_f32_e32 v113, v109
	s_nop 0
	v_pk_mul_f32 v[112:113], v[114:115], v[112:113]
	s_nop 0
	v_pk_mul_f32 v[110:111], v[112:113], v[110:111]
	s_nop 0
	v_cvt_pk_bf16_f32 v109, v110, v111
	v_mul_f32_e32 v110, 0xbfb8aa3b, v104
	v_mul_f32_e32 v111, 0xbfb8aa3b, v105
	v_exp_f32_e32 v110, v110
	v_exp_f32_e32 v111, v111
	v_add_f32_e32 v110, 1.0, v110
	v_add_f32_e32 v111, 1.0, v111
	v_rcp_f32_e32 v110, v110
	v_rcp_f32_e32 v111, v111
	s_nop 0
	v_pk_mul_f32 v[104:105], v[104:105], v[110:111]
	s_nop 0
	v_pk_mul_f32 v[100:101], v[104:105], v[100:101]
	s_nop 0
	v_cvt_pk_bf16_f32 v110, v100, v101
	v_mul_f32_e32 v100, 0xbfb8aa3b, v106
	v_mul_f32_e32 v101, 0xbfb8aa3b, v107
	v_exp_f32_e32 v100, v100
	v_exp_f32_e32 v101, v101
	v_add_f32_e32 v100, 1.0, v100
	v_add_f32_e32 v101, 1.0, v101
	v_rcp_f32_e32 v100, v100
	v_rcp_f32_e32 v101, v101
	s_nop 0
	v_pk_mul_f32 v[100:101], v[106:107], v[100:101]
	s_nop 0
	v_pk_mul_f32 v[100:101], v[100:101], v[102:103]
	s_nop 0
	v_cvt_pk_bf16_f32 v111, v100, v101
	v_or_b32_e32 v100, 16, v146
	v_mad_i64_i32 v[100:101], s[30:31], v100, s3, v[116:117]
	v_lshl_add_u64 v[100:101], v[100:101], 0, v[118:119]
	global_store_dwordx4 v[100:101], v[108:111], off
	v_mul_f32_e32 v100, 0xbfb8aa3b, v96
	v_mul_f32_e32 v101, 0xbfb8aa3b, v97
	v_exp_f32_e32 v100, v100
	v_exp_f32_e32 v101, v101
	v_add_f32_e32 v100, 1.0, v100
	v_add_f32_e32 v101, 1.0, v101
	v_rcp_f32_e32 v100, v100
	v_rcp_f32_e32 v101, v101
	s_nop 0
	v_pk_mul_f32 v[96:97], v[96:97], v[100:101]
	s_nop 0
	v_pk_mul_f32 v[92:93], v[96:97], v[92:93]
	s_nop 0
	v_cvt_pk_bf16_f32 v92, v92, v93
	v_mul_f32_e32 v93, 0xbfb8aa3b, v98
	v_exp_f32_e32 v93, v93
	s_nop 0
	v_add_f32_e32 v93, 1.0, v93
	v_rcp_f32_e32 v96, v93
	v_mul_f32_e32 v93, 0xbfb8aa3b, v99
	v_exp_f32_e32 v93, v93
	s_nop 0
	v_add_f32_e32 v93, 1.0, v93
	v_rcp_f32_e32 v97, v93
	s_nop 0
	v_pk_mul_f32 v[96:97], v[98:99], v[96:97]
	s_nop 0
	v_pk_mul_f32 v[94:95], v[96:97], v[94:95]
	s_nop 0
	v_cvt_pk_bf16_f32 v93, v94, v95
	v_mul_f32_e32 v94, 0xbfb8aa3b, v88
	v_mul_f32_e32 v95, 0xbfb8aa3b, v89
	v_exp_f32_e32 v94, v94
	v_exp_f32_e32 v95, v95
	v_add_f32_e32 v94, 1.0, v94
	v_add_f32_e32 v95, 1.0, v95
	v_rcp_f32_e32 v94, v94
	v_rcp_f32_e32 v95, v95
	s_nop 0
	v_pk_mul_f32 v[88:89], v[88:89], v[94:95]
	s_nop 0
	v_pk_mul_f32 v[84:85], v[88:89], v[84:85]
	s_nop 0
	v_cvt_pk_bf16_f32 v94, v84, v85
	v_mul_f32_e32 v84, 0xbfb8aa3b, v90
	v_mul_f32_e32 v85, 0xbfb8aa3b, v91
	v_exp_f32_e32 v84, v84
	v_exp_f32_e32 v85, v85
	v_add_f32_e32 v84, 1.0, v84
	v_add_f32_e32 v85, 1.0, v85
	v_rcp_f32_e32 v84, v84
	v_rcp_f32_e32 v85, v85
	s_nop 0
	v_pk_mul_f32 v[84:85], v[90:91], v[84:85]
	s_nop 0
	v_pk_mul_f32 v[84:85], v[84:85], v[86:87]
	s_nop 0
	v_cvt_pk_bf16_f32 v95, v84, v85
	v_or_b32_e32 v84, 32, v146
	v_mad_i64_i32 v[84:85], s[30:31], v84, s3, v[116:117]
	v_lshl_add_u64 v[84:85], v[84:85], 0, v[118:119]
	global_store_dwordx4 v[84:85], v[92:95], off
	v_mul_f32_e32 v84, 0xbfb8aa3b, v80
	v_mul_f32_e32 v85, 0xbfb8aa3b, v81
	v_exp_f32_e32 v84, v84
	v_exp_f32_e32 v85, v85
	v_add_f32_e32 v84, 1.0, v84
	v_add_f32_e32 v85, 1.0, v85
	v_rcp_f32_e32 v84, v84
	v_rcp_f32_e32 v85, v85
	s_nop 0
	v_pk_mul_f32 v[80:81], v[80:81], v[84:85]
	s_nop 0
	v_pk_mul_f32 v[76:77], v[80:81], v[76:77]
	s_nop 0
	v_cvt_pk_bf16_f32 v76, v76, v77
	v_mul_f32_e32 v77, 0xbfb8aa3b, v82
	v_exp_f32_e32 v77, v77
	s_nop 0
	v_add_f32_e32 v77, 1.0, v77
	v_rcp_f32_e32 v80, v77
	v_mul_f32_e32 v77, 0xbfb8aa3b, v83
	v_exp_f32_e32 v77, v77
	s_nop 0
	v_add_f32_e32 v77, 1.0, v77
	v_rcp_f32_e32 v81, v77
	s_nop 0
	v_pk_mul_f32 v[80:81], v[82:83], v[80:81]
	s_nop 0
	v_pk_mul_f32 v[78:79], v[80:81], v[78:79]
	s_nop 0
	v_cvt_pk_bf16_f32 v77, v78, v79
	v_mul_f32_e32 v78, 0xbfb8aa3b, v72
	v_mul_f32_e32 v79, 0xbfb8aa3b, v73
	v_exp_f32_e32 v78, v78
	v_exp_f32_e32 v79, v79
	v_add_f32_e32 v78, 1.0, v78
	v_add_f32_e32 v79, 1.0, v79
	v_rcp_f32_e32 v78, v78
	v_rcp_f32_e32 v79, v79
	s_nop 0
	v_pk_mul_f32 v[72:73], v[72:73], v[78:79]
	s_nop 0
	v_pk_mul_f32 v[68:69], v[72:73], v[68:69]
	s_nop 0
	v_cvt_pk_bf16_f32 v78, v68, v69
	v_mul_f32_e32 v68, 0xbfb8aa3b, v74
	v_mul_f32_e32 v69, 0xbfb8aa3b, v75
	v_exp_f32_e32 v68, v68
	v_exp_f32_e32 v69, v69
	v_add_f32_e32 v68, 1.0, v68
	v_add_f32_e32 v69, 1.0, v69
	v_rcp_f32_e32 v68, v68
	v_rcp_f32_e32 v69, v69
	s_nop 0
	v_pk_mul_f32 v[68:69], v[74:75], v[68:69]
	s_nop 0
	v_pk_mul_f32 v[68:69], v[68:69], v[70:71]
	v_add_u32_e32 v70, 0x80, v146
	v_cvt_pk_bf16_f32 v79, v68, v69
	v_or_b32_e32 v68, 48, v146
	v_mad_i64_i32 v[68:69], s[30:31], v68, s3, v[116:117]
	v_lshl_add_u64 v[68:69], v[68:69], 0, v[118:119]
	global_store_dwordx4 v[68:69], v[76:79], off
	v_mul_f32_e32 v68, 0xbfb8aa3b, v64
	v_mul_f32_e32 v69, 0xbfb8aa3b, v65
	v_exp_f32_e32 v68, v68
	v_exp_f32_e32 v69, v69
	v_add_f32_e32 v68, 1.0, v68
; DI unsigned cvt_pk_bf16(float lo, float hi) { const f32x2 v = {lo, hi}; const bf16x2_t r = __builtin_convertvector(v, bf16x2_t); return __builtin_bit_cast(unsigned, r); }
; #define PG8_WAIT_V(n) asm volatile("s_waitcnt vmcnt(" #n ")" ::: "memory")
; #define PG8_BAR __builtin_amdgcn_s_barrier()
; DI float silu_f(float g) { return g * __builtin_amdgcn_rcpf(1.0f + __expf(-g)); }
; template <class Epi>
; DI void gemm_phase(LAS unsigned char* lds, const Gemm g, const Epi& E) {
;     ...
;     if (!has_next) break;
; #pragma unroll
;     for (int a = 0; a < 2; ++a)
; #pragma unroll
;       for (int b = 0; b < 2; ++b)
; #pragma unroll
;         for (int m = 0; m < 4; ++m)
; #pragma unroll
;           for (int n = 0; n < 2; ++n) acc[a][b][m][n] = (f32x4){0.f, 0.f, 0.f, 0.f};
;     cur = nxt; cA = nA; cB = nB; ++ui;
;   }
;   PG8_WAIT_V(0);
;   if (wr == 0) PG8_BAR;
;   PG8_BAR;
;   DI void operator()(const f32x4 (&acc)[2][2][4][2], const Unit& u, int wr, int wc, int fr, int fq) const {
;     const int row0 = u.pm * BM + wr * 64 + fr, col0 = u.pn * HALF + wc * 32 + 8 * fq;
; #pragma unroll
;     for (int ai = 0; ai < 2; ++ai)
; #pragma unroll
;       for (int m = 0; m < 4; ++m) {
;         const f32x4 g0 = acc[ai][0][m][0], g1 = acc[ai][0][m][1], u0 = acc[ai][1][m][0], u1 = acc[ai][1][m][1];
;         u32x4 w;
;         w.x = cvt_pk_bf16(silu_f(g0[0]) * u0[0], silu_f(g0[1]) * u0[1]); w.y = cvt_pk_bf16(silu_f(g0[2]) * u0[2], silu_f(g0[3]) * u0[3]);
;         w.z = cvt_pk_bf16(silu_f(g1[0]) * u1[0], silu_f(g1[1]) * u1[1]); w.w = cvt_pk_bf16(silu_f(g1[2]) * u1[2], silu_f(g1[3]) * u1[3]);
;         *(u32x4*)(H + (size_t)(row0 + ai * HALF + m * 16) * DFF + col0) = w;
;       }
	v_add_f32_e32 v69, 1.0, v69
	v_rcp_f32_e32 v68, v68
	v_rcp_f32_e32 v69, v69
	s_nop 0
	v_pk_mul_f32 v[64:65], v[64:65], v[68:69]
	s_nop 0
	v_pk_mul_f32 v[60:61], v[64:65], v[60:61]
	s_nop 0
	v_cvt_pk_bf16_f32 v60, v60, v61
	v_mul_f32_e32 v61, 0xbfb8aa3b, v66
	v_exp_f32_e32 v61, v61
	s_nop 0
	v_add_f32_e32 v61, 1.0, v61
	v_rcp_f32_e32 v64, v61
	v_mul_f32_e32 v61, 0xbfb8aa3b, v67
	v_exp_f32_e32 v61, v61
	s_nop 0
	v_add_f32_e32 v61, 1.0, v61
	v_rcp_f32_e32 v65, v61
	s_nop 0
	v_pk_mul_f32 v[64:65], v[66:67], v[64:65]
	s_nop 0
	v_pk_mul_f32 v[62:63], v[64:65], v[62:63]
	s_nop 0
	v_cvt_pk_bf16_f32 v61, v62, v63
	v_mul_f32_e32 v62, 0xbfb8aa3b, v56
	v_mul_f32_e32 v63, 0xbfb8aa3b, v57
	v_exp_f32_e32 v62, v62
	v_exp_f32_e32 v63, v63
	v_add_f32_e32 v62, 1.0, v62
	v_add_f32_e32 v63, 1.0, v63
	v_rcp_f32_e32 v62, v62
	v_rcp_f32_e32 v63, v63
	s_nop 0
	v_pk_mul_f32 v[56:57], v[56:57], v[62:63]
	s_nop 0
	v_pk_mul_f32 v[52:53], v[56:57], v[52:53]
	s_nop 0
	v_cvt_pk_bf16_f32 v62, v52, v53
	v_mul_f32_e32 v52, 0xbfb8aa3b, v58
	v_mul_f32_e32 v53, 0xbfb8aa3b, v59
	v_exp_f32_e32 v52, v52
	v_exp_f32_e32 v53, v53
	v_add_f32_e32 v52, 1.0, v52
	v_add_f32_e32 v53, 1.0, v53
	v_rcp_f32_e32 v52, v52
	v_rcp_f32_e32 v53, v53
	s_nop 0
	v_pk_mul_f32 v[52:53], v[58:59], v[52:53]
	s_nop 0
	v_pk_mul_f32 v[52:53], v[52:53], v[54:55]
	s_nop 0
	v_cvt_pk_bf16_f32 v63, v52, v53
	v_mad_i64_i32 v[52:53], s[30:31], v70, s3, v[116:117]
	v_lshl_add_u64 v[52:53], v[52:53], 0, v[118:119]
	global_store_dwordx4 v[52:53], v[60:63], off
	v_mul_f32_e32 v52, 0xbfb8aa3b, v48
	v_mul_f32_e32 v53, 0xbfb8aa3b, v49
	v_exp_f32_e32 v52, v52
	v_exp_f32_e32 v53, v53
	v_add_f32_e32 v52, 1.0, v52
	v_add_f32_e32 v53, 1.0, v53
	v_rcp_f32_e32 v52, v52
	v_rcp_f32_e32 v53, v53
	s_nop 0
	v_pk_mul_f32 v[48:49], v[48:49], v[52:53]
	s_nop 0
	v_pk_mul_f32 v[44:45], v[48:49], v[44:45]
	s_nop 0
	v_cvt_pk_bf16_f32 v44, v44, v45
	v_mul_f32_e32 v45, 0xbfb8aa3b, v50
	v_exp_f32_e32 v45, v45
	s_nop 0
	v_add_f32_e32 v45, 1.0, v45
	v_rcp_f32_e32 v48, v45
	v_mul_f32_e32 v45, 0xbfb8aa3b, v51
	v_exp_f32_e32 v45, v45
	s_nop 0
	v_add_f32_e32 v45, 1.0, v45
	v_rcp_f32_e32 v49, v45
	s_nop 0
	v_pk_mul_f32 v[48:49], v[50:51], v[48:49]
	s_nop 0
	v_pk_mul_f32 v[46:47], v[48:49], v[46:47]
	s_nop 0
	v_cvt_pk_bf16_f32 v45, v46, v47
	v_mul_f32_e32 v46, 0xbfb8aa3b, v40
	v_mul_f32_e32 v47, 0xbfb8aa3b, v41
	v_exp_f32_e32 v46, v46
	v_exp_f32_e32 v47, v47
	v_add_f32_e32 v46, 1.0, v46
	v_add_f32_e32 v47, 1.0, v47
	v_rcp_f32_e32 v46, v46
	v_rcp_f32_e32 v47, v47
	s_nop 0
	v_pk_mul_f32 v[40:41], v[40:41], v[46:47]
	s_nop 0
	v_pk_mul_f32 v[36:37], v[40:41], v[36:37]
	s_nop 0
	v_cvt_pk_bf16_f32 v46, v36, v37
	v_mul_f32_e32 v36, 0xbfb8aa3b, v42
	v_mul_f32_e32 v37, 0xbfb8aa3b, v43
	v_exp_f32_e32 v36, v36
	v_exp_f32_e32 v37, v37
	v_add_f32_e32 v36, 1.0, v36
	v_add_f32_e32 v37, 1.0, v37
	v_rcp_f32_e32 v36, v36
	v_rcp_f32_e32 v37, v37
	s_nop 0
	v_pk_mul_f32 v[36:37], v[42:43], v[36:37]
	s_nop 0
	v_pk_mul_f32 v[36:37], v[36:37], v[38:39]
	s_nop 0
	v_cvt_pk_bf16_f32 v47, v36, v37
	v_add_u32_e32 v36, 0x90, v146
	v_mad_i64_i32 v[36:37], s[30:31], v36, s3, v[116:117]
	v_lshl_add_u64 v[36:37], v[36:37], 0, v[118:119]
	global_store_dwordx4 v[36:37], v[44:47], off
	v_mul_f32_e32 v36, 0xbfb8aa3b, v32
	v_mul_f32_e32 v37, 0xbfb8aa3b, v33
	v_exp_f32_e32 v36, v36
	v_exp_f32_e32 v37, v37
	v_add_f32_e32 v36, 1.0, v36
	v_add_f32_e32 v37, 1.0, v37
	v_rcp_f32_e32 v36, v36
	v_rcp_f32_e32 v37, v37
	s_nop 0
	v_pk_mul_f32 v[32:33], v[32:33], v[36:37]
	s_nop 0
	v_pk_mul_f32 v[28:29], v[32:33], v[28:29]
	s_nop 0
	v_cvt_pk_bf16_f32 v28, v28, v29
	v_mul_f32_e32 v29, 0xbfb8aa3b, v34
	v_exp_f32_e32 v29, v29
	s_nop 0
	v_add_f32_e32 v29, 1.0, v29
	v_rcp_f32_e32 v32, v29
	v_mul_f32_e32 v29, 0xbfb8aa3b, v35
	v_exp_f32_e32 v29, v29
	s_nop 0
	v_add_f32_e32 v29, 1.0, v29
	v_rcp_f32_e32 v33, v29
	s_nop 0
	v_pk_mul_f32 v[32:33], v[34:35], v[32:33]
	s_nop 0
	v_pk_mul_f32 v[30:31], v[32:33], v[30:31]
	s_nop 0
	v_cvt_pk_bf16_f32 v29, v30, v31
	v_mul_f32_e32 v30, 0xbfb8aa3b, v24
	v_mul_f32_e32 v31, 0xbfb8aa3b, v25
	v_exp_f32_e32 v30, v30
	v_exp_f32_e32 v31, v31
	v_add_f32_e32 v30, 1.0, v30
	v_add_f32_e32 v31, 1.0, v31
	v_rcp_f32_e32 v30, v30
	v_rcp_f32_e32 v31, v31
	s_nop 0
	v_pk_mul_f32 v[24:25], v[24:25], v[30:31]
	s_nop 0
	v_pk_mul_f32 v[20:21], v[24:25], v[20:21]
	s_nop 0
	v_cvt_pk_bf16_f32 v30, v20, v21
	v_mul_f32_e32 v20, 0xbfb8aa3b, v26
	v_mul_f32_e32 v21, 0xbfb8aa3b, v27
	v_exp_f32_e32 v20, v20
	v_exp_f32_e32 v21, v21
	v_add_f32_e32 v20, 1.0, v20
	v_add_f32_e32 v21, 1.0, v21
	v_rcp_f32_e32 v20, v20
	v_rcp_f32_e32 v21, v21
	s_nop 0
	v_pk_mul_f32 v[20:21], v[26:27], v[20:21]
	s_nop 0
	v_pk_mul_f32 v[20:21], v[20:21], v[22:23]
	s_nop 0
	v_cvt_pk_bf16_f32 v31, v20, v21
	v_add_u32_e32 v20, 0xa0, v146
	v_mad_i64_i32 v[20:21], s[30:31], v20, s3, v[116:117]
	v_lshl_add_u64 v[20:21], v[20:21], 0, v[118:119]
	global_store_dwordx4 v[20:21], v[28:31], off
	v_mul_f32_e32 v20, 0xbfb8aa3b, v16
	v_mul_f32_e32 v21, 0xbfb8aa3b, v17
	v_exp_f32_e32 v20, v20
	v_exp_f32_e32 v21, v21
	v_add_f32_e32 v20, 1.0, v20
	v_add_f32_e32 v21, 1.0, v21
	v_rcp_f32_e32 v20, v20
	v_rcp_f32_e32 v21, v21
	s_nop 0
	v_pk_mul_f32 v[16:17], v[16:17], v[20:21]
	s_nop 0
	v_pk_mul_f32 v[12:13], v[16:17], v[12:13]
	s_nop 0
	v_cvt_pk_bf16_f32 v12, v12, v13
	v_mul_f32_e32 v13, 0xbfb8aa3b, v18
	v_exp_f32_e32 v13, v13
	s_nop 0
	v_add_f32_e32 v13, 1.0, v13
	v_rcp_f32_e32 v16, v13
	v_mul_f32_e32 v13, 0xbfb8aa3b, v19
	v_exp_f32_e32 v13, v13
	s_nop 0
	v_add_f32_e32 v13, 1.0, v13
	v_rcp_f32_e32 v17, v13
	s_nop 0
	v_pk_mul_f32 v[16:17], v[18:19], v[16:17]
	s_nop 0
	v_pk_mul_f32 v[14:15], v[16:17], v[14:15]
	s_nop 0
	v_cvt_pk_bf16_f32 v13, v14, v15
	v_mul_f32_e32 v14, 0xbfb8aa3b, v8
	v_mul_f32_e32 v15, 0xbfb8aa3b, v9
	v_exp_f32_e32 v14, v14
	v_exp_f32_e32 v15, v15
	v_add_f32_e32 v14, 1.0, v14
	v_add_f32_e32 v15, 1.0, v15
	v_rcp_f32_e32 v14, v14
	v_rcp_f32_e32 v15, v15
	s_nop 0
	v_pk_mul_f32 v[8:9], v[8:9], v[14:15]
	s_nop 0
	v_pk_mul_f32 v[4:5], v[8:9], v[4:5]
	s_nop 0
	v_cvt_pk_bf16_f32 v14, v4, v5
	v_mul_f32_e32 v4, 0xbfb8aa3b, v10
	v_mul_f32_e32 v5, 0xbfb8aa3b, v11
	v_exp_f32_e32 v4, v4
	v_exp_f32_e32 v5, v5
	v_add_f32_e32 v4, 1.0, v4
	v_add_f32_e32 v5, 1.0, v5
	v_rcp_f32_e32 v4, v4
	v_rcp_f32_e32 v5, v5
	s_nop 0
	v_pk_mul_f32 v[4:5], v[10:11], v[4:5]
	s_nop 0
	v_pk_mul_f32 v[4:5], v[4:5], v[6:7]
	s_nop 0
	v_cvt_pk_bf16_f32 v15, v4, v5
	v_add_u32_e32 v4, 0xb0, v146
	v_mad_i64_i32 v[4:5], s[30:31], v4, s3, v[116:117]
	v_lshl_add_u64 v[4:5], v[4:5], 0, v[118:119]
	s_mov_b64 s[30:31], s[18:19]
	global_store_dwordx4 v[4:5], v[12:15], off
	s_cbranch_vccz .LBB0_187
	s_waitcnt vmcnt(0)
	s_cmpk_gt_u32 s25, 0xff
	s_cbranch_scc1 .LBB0_194
	s_barrier

; #define PG8_STAGE(bufoff, gbase, voff) do { _Pragma("unroll") for (int _i = 0; _i < 2; ++_i) \
;     __builtin_amdgcn_global_load_lds((const unsigned*)((const char*)(gbase) + (voff)[_i]), (LAS unsigned*)(lds + (bufoff) + ldsw + _i * 8192), 16, 0, 0); } while (0)
; #define PG8_LDA(dst, b, h) do { _Pragma("unroll") for (int m = 0; m < 4; ++m) _Pragma("unroll") for (int k = 0; k < 2; ++k) dst[m][k] = *(const LAS bf16x8*)(lds + PG8_SA(b, h) + aoff + m * 2048 + k * 1024); } while (0)
; #define PG8_LDB(dst, b, h) do { _Pragma("unroll") for (int n = 0; n < 2; ++n) _Pragma("unroll") for (int k = 0; k < 2; ++k) dst[n][k] = *(const LAS bf16x8*)(lds + PG8_SB(b, h) + boff + n * 2048 + k * 1024); } while (0)
; #define PG8_MMA(ai, bj, At, Bt) do { __builtin_amdgcn_s_setprio(1); _Pragma("unroll") for (int m = 0; m < 4; ++m) _Pragma("unroll") for (int n = 0; n < 2; ++n) _Pragma("unroll") for (int k = 0; k < 2; ++k) \
;     acc[ai][bj][m][n] = __builtin_amdgcn_mfma_f32_16x16x32_bf16(Bt[n][k], At[m][k], acc[ai][bj][m][n], 0, 0, 0); __builtin_amdgcn_s_setprio(0); } while (0)
; #define PG8_WAIT_V(n) asm volatile("s_waitcnt vmcnt(" #n ")" ::: "memory")
; #define PG8_BAR __builtin_amdgcn_s_barrier()
; template <class Epi>
; DI void gemm_phase(LAS unsigned char* lds, const Gemm g, const Epi& E) {
;     ...
;     for (int t = 0; t < nt; t += 2) {
;       const bool last = (t == nt - 2);
;       const char* a1 = cA + (size_t)(t + 1) * kstep;
;       const char* a2 = last ? nA : cA + (size_t)(t + 2) * kstep; const char* b2 = last ? nB : cB + (size_t)(t + 2) * kstep;
;       const char* a3 = a2 + kstep; const char* b3 = b2 + kstep;
;       PG8_LDB(B0, 0, 0); PG8_SCHED; PG8_LDA(At, 0, 0); PG8_STAGE(PG8_SA(1, 1), a1 + hstepA, voffA);
;       PG8_WAIT_L(8); PG8_BAR; PG8_WAIT_L(0); PG8_MMA(0, 0, At, B0); PG8_BAR; PG8_SCHED;
;       PG8_LDB(B1, 0, 1); PG8_STAGE(PG8_SB(0, 0), b2, voffB);
;       PG8_BAR; PG8_WAIT_L(0); PG8_MMA(0, 1, At, B1); PG8_BAR;
;       PG8_LDA(At, 0, 1); PG8_STAGE(PG8_SA(0, 0), a2, voffA);
;       PG8_BAR; PG8_WAIT_L(0); PG8_MMA(1, 0, At, B0); PG8_BAR; PG8_SCHED;
;       PG8_STAGE(PG8_SB(0, 1), b2 + hstepB, voffB);
;       PG8_WAIT_V(6); PG8_BAR; PG8_MMA(1, 1, At, B1); PG8_BAR;
;       PG8_LDB(B0, 1, 0); PG8_SCHED; PG8_LDA(At, 1, 0); PG8_STAGE(PG8_SA(0, 1), a2 + hstepA, voffA);
;       PG8_WAIT_L(8); PG8_BAR; PG8_WAIT_L(0); PG8_MMA(0, 0, At, B0); PG8_BAR; PG8_SCHED;
.LBB0_225:
	s_add_u32 s44, s42, 0xfff80080
	s_addc_u32 s45, s43, -1
	s_add_i32 s67, 0, 0x10000
	s_cmp_eq_u32 s66, 28
	s_cselect_b32 s47, s27, s45
	s_cselect_b32 s46, s41, s44
	s_cselect_b32 s45, s23, s65
	s_cselect_b32 s44, s63, s64
	v_lshl_add_u64 v[148:149], s[42:43], 0, v[144:145]
	s_add_i32 m0, s55, 0xc000
	ds_read_b128 v[188:191], v154
	ds_read_b128 v[192:195], v154 offset:1024
	ds_read_b128 v[196:199], v154 offset:2048
	ds_read_b128 v[200:203], v154 offset:3072
	ds_read_b128 v[208:211], v154 offset:4096
	ds_read_b128 v[212:215], v154 offset:5120
	ds_read_b128 v[216:219], v154 offset:6144
	ds_read_b128 v[220:223], v154 offset:7168
	global_load_lds_dwordx4 v[148:149], off
	v_lshl_add_u64 v[148:149], s[42:43], 0, v[146:147]
	s_add_i32 m0, s55, 0xe000
	s_nop 0
	global_load_lds_dwordx4 v[148:149], off
	s_waitcnt lgkmcnt(8)
	s_barrier
	s_waitcnt lgkmcnt(0)
	s_setprio 1
	s_waitcnt lgkmcnt(0)
	v_mfma_f32_16x16x32_bf16 v[128:131], v[156:159], v[188:191], v[128:131]
	v_mfma_f32_16x16x32_bf16 v[124:127], v[180:183], v[188:191], v[124:127]
	v_mfma_f32_16x16x32_bf16 v[120:123], v[156:159], v[196:199], v[120:123]
	v_mfma_f32_16x16x32_bf16 v[116:119], v[180:183], v[196:199], v[116:119]
	v_mfma_f32_16x16x32_bf16 v[104:107], v[156:159], v[208:211], v[104:107]
	v_mfma_f32_16x16x32_bf16 v[100:103], v[180:183], v[208:211], v[100:103]
	v_mfma_f32_16x16x32_bf16 v[88:91], v[156:159], v[216:219], v[88:91]
	v_mfma_f32_16x16x32_bf16 v[84:87], v[180:183], v[216:219], v[84:87]
	v_mfma_f32_16x16x32_bf16 v[128:131], v[160:163], v[192:195], v[128:131]
	v_mfma_f32_16x16x32_bf16 v[124:127], v[184:187], v[192:195], v[124:127]
	v_mfma_f32_16x16x32_bf16 v[120:123], v[160:163], v[200:203], v[120:123]
	v_mfma_f32_16x16x32_bf16 v[116:119], v[184:187], v[200:203], v[116:119]
	v_mfma_f32_16x16x32_bf16 v[104:107], v[160:163], v[212:215], v[104:107]
	v_mfma_f32_16x16x32_bf16 v[100:103], v[184:187], v[212:215], v[100:103]
	s_setprio 2
	s_barrier
	v_mfma_f32_16x16x32_bf16 v[88:91], v[160:163], v[220:223], v[88:91]
	v_mfma_f32_16x16x32_bf16 v[84:87], v[184:187], v[220:223], v[84:87]
	s_setprio 0
	s_add_i32 s70, 0, 0x14000
	s_add_i32 s67, s67, s54
	v_lshl_add_u64 v[148:149], s[44:45], 0, v[136:137]
	s_mov_b32 m0, s67
	ds_read_b128 v[224:227], v248 offset:16384
	ds_read_b128 v[228:231], v248 offset:17408
	ds_read_b128 v[232:235], v248 offset:18432
	ds_read_b128 v[236:239], v248 offset:19456
	global_load_lds_dwordx4 v[148:149], off
	v_lshl_add_u64 v[240:241], s[44:45], 0, v[132:133]
	s_add_i32 m0, s67, 0x2000
	s_nop 0
	global_load_lds_dwordx4 v[240:241], off
	s_barrier
	s_waitcnt lgkmcnt(0)
	s_setprio 1
	s_waitcnt lgkmcnt(0)
	v_mfma_f32_16x16x32_bf16 v[112:115], v[224:227], v[188:191], v[112:115]
	v_mfma_f32_16x16x32_bf16 v[108:111], v[232:235], v[188:191], v[108:111]
	v_mfma_f32_16x16x32_bf16 v[96:99], v[224:227], v[196:199], v[96:99]
	v_mfma_f32_16x16x32_bf16 v[92:95], v[232:235], v[196:199], v[92:95]
	v_mfma_f32_16x16x32_bf16 v[80:83], v[224:227], v[208:211], v[80:83]
	v_mfma_f32_16x16x32_bf16 v[76:79], v[232:235], v[208:211], v[76:79]
	v_mfma_f32_16x16x32_bf16 v[72:75], v[224:227], v[216:219], v[72:75]
	v_mfma_f32_16x16x32_bf16 v[68:71], v[232:235], v[216:219], v[68:71]
	v_mfma_f32_16x16x32_bf16 v[112:115], v[228:231], v[192:195], v[112:115]
	v_mfma_f32_16x16x32_bf16 v[108:111], v[236:239], v[192:195], v[108:111]
	v_mfma_f32_16x16x32_bf16 v[96:99], v[228:231], v[200:203], v[96:99]
	v_mfma_f32_16x16x32_bf16 v[92:95], v[236:239], v[200:203], v[92:95]
	v_mfma_f32_16x16x32_bf16 v[80:83], v[228:231], v[212:215], v[80:83]
	v_mfma_f32_16x16x32_bf16 v[76:79], v[236:239], v[212:215], v[76:79]
	s_setprio 2
	s_barrier
	v_mfma_f32_16x16x32_bf16 v[72:75], v[228:231], v[220:223], v[72:75]
	v_mfma_f32_16x16x32_bf16 v[68:71], v[236:239], v[220:223], v[68:71]
	s_setprio 0
	s_mov_b32 m0, s55
	v_lshl_add_u64 v[242:243], s[46:47], 0, v[138:139]
	ds_read_b128 v[188:191], v154 offset:16384
	ds_read_b128 v[192:195], v154 offset:17408
	ds_read_b128 v[196:199], v154 offset:18432
	ds_read_b128 v[200:203], v154 offset:19456
	ds_read_b128 v[208:211], v154 offset:20480
	ds_read_b128 v[212:215], v154 offset:21504
	ds_read_b128 v[216:219], v154 offset:22528
	ds_read_b128 v[220:223], v154 offset:23552
	global_load_lds_dwordx4 v[242:243], off
	v_lshl_add_u64 v[244:245], s[46:47], 0, v[134:135]
	s_mov_b32 m0, s56
	s_nop 0
	global_load_lds_dwordx4 v[244:245], off
	s_waitcnt vmcnt(10)
	s_barrier
	s_waitcnt lgkmcnt(0)
	s_setprio 1
	s_waitcnt lgkmcnt(0)
	v_mfma_f32_16x16x32_bf16 v[64:67], v[156:159], v[188:191], v[64:67]
	v_mfma_f32_16x16x32_bf16 v[60:63], v[180:183], v[188:191], v[60:63]
	v_mfma_f32_16x16x32_bf16 v[56:59], v[156:159], v[196:199], v[56:59]
	v_mfma_f32_16x16x32_bf16 v[52:55], v[180:183], v[196:199], v[52:55]
	v_mfma_f32_16x16x32_bf16 v[40:43], v[156:159], v[208:211], v[40:43]
	v_mfma_f32_16x16x32_bf16 v[36:39], v[180:183], v[208:211], v[36:39]
	v_mfma_f32_16x16x32_bf16 v[24:27], v[156:159], v[216:219], v[24:27]
	v_mfma_f32_16x16x32_bf16 v[20:23], v[180:183], v[216:219], v[20:23]
	v_mfma_f32_16x16x32_bf16 v[64:67], v[160:163], v[192:195], v[64:67]
	v_mfma_f32_16x16x32_bf16 v[60:63], v[184:187], v[192:195], v[60:63]
	v_mfma_f32_16x16x32_bf16 v[56:59], v[160:163], v[200:203], v[56:59]
	v_mfma_f32_16x16x32_bf16 v[52:55], v[184:187], v[200:203], v[52:55]
	v_mfma_f32_16x16x32_bf16 v[40:43], v[160:163], v[212:215], v[40:43]
	v_mfma_f32_16x16x32_bf16 v[36:39], v[184:187], v[212:215], v[36:39]
	s_setprio 2
	s_barrier
; #define PG8_STAGE(bufoff, gbase, voff) do { _Pragma("unroll") for (int _i = 0; _i < 2; ++_i) \
;     __builtin_amdgcn_global_load_lds((const unsigned*)((const char*)(gbase) + (voff)[_i]), (LAS unsigned*)(lds + (bufoff) + ldsw + _i * 8192), 16, 0, 0); } while (0)
; #define PG8_LDA(dst, b, h) do { _Pragma("unroll") for (int m = 0; m < 4; ++m) _Pragma("unroll") for (int k = 0; k < 2; ++k) dst[m][k] = *(const LAS bf16x8*)(lds + PG8_SA(b, h) + aoff + m * 2048 + k * 1024); } while (0)
; #define PG8_LDB(dst, b, h) do { _Pragma("unroll") for (int n = 0; n < 2; ++n) _Pragma("unroll") for (int k = 0; k < 2; ++k) dst[n][k] = *(const LAS bf16x8*)(lds + PG8_SB(b, h) + boff + n * 2048 + k * 1024); } while (0)
; #define PG8_MMA(ai, bj, At, Bt) do { __builtin_amdgcn_s_setprio(1); _Pragma("unroll") for (int m = 0; m < 4; ++m) _Pragma("unroll") for (int n = 0; n < 2; ++n) _Pragma("unroll") for (int k = 0; k < 2; ++k) \
;     acc[ai][bj][m][n] = __builtin_amdgcn_mfma_f32_16x16x32_bf16(Bt[n][k], At[m][k], acc[ai][bj][m][n], 0, 0, 0); __builtin_amdgcn_s_setprio(0); } while (0)
; #define PG8_WAIT_V(n) asm volatile("s_waitcnt vmcnt(" #n ")" ::: "memory")
; #define PG8_WAIT_L(n) asm volatile("s_waitcnt lgkmcnt(" #n ")" ::: "memory")
; #define PG8_BAR __builtin_amdgcn_s_barrier()
; #define PG8_SCHED __builtin_amdgcn_sched_barrier(0)
; template <class Epi>
; DI void gemm_phase(LAS unsigned char* lds, const Gemm g, const Epi& E) {
;     ...
;       PG8_WAIT_V(6); PG8_BAR; PG8_MMA(1, 1, At, B1); PG8_BAR;
;       PG8_LDB(B0, 1, 0); PG8_SCHED; PG8_LDA(At, 1, 0); PG8_STAGE(PG8_SA(0, 1), a2 + hstepA, voffA);
;       PG8_WAIT_L(8); PG8_BAR; PG8_WAIT_L(0); PG8_MMA(0, 0, At, B0); PG8_BAR; PG8_SCHED;
;       PG8_LDB(B1, 1, 1); PG8_STAGE(PG8_SB(1, 0), b3, voffB);
;       PG8_BAR; PG8_WAIT_L(0); PG8_MMA(0, 1, At, B1); PG8_BAR;
;       PG8_LDA(At, 1, 1); PG8_STAGE(PG8_SA(1, 0), a3, voffA);
;       PG8_BAR; PG8_WAIT_L(0); PG8_MMA(1, 0, At, B0); PG8_BAR; PG8_SCHED;
	v_mfma_f32_16x16x32_bf16 v[24:27], v[160:163], v[220:223], v[24:27]
	v_mfma_f32_16x16x32_bf16 v[20:23], v[184:187], v[220:223], v[20:23]
	s_setprio 0
	ds_read_b128 v[156:159], v248 offset:32768
	ds_read_b128 v[160:163], v248 offset:33792
	ds_read_b128 v[180:183], v248 offset:34816
	ds_read_b128 v[184:187], v248 offset:35840
	s_add_u32 s68, s44, 0x80000
	s_addc_u32 s69, s45, 0
	s_add_i32 s67, s70, s54
	v_lshl_add_u64 v[246:247], s[68:69], 0, v[136:137]
	s_mov_b32 m0, s67
	s_nop 0
	global_load_lds_dwordx4 v[246:247], off
	v_lshl_add_u64 v[246:247], s[68:69], 0, v[132:133]
	s_add_i32 m0, s67, 0x2000
	s_nop 0
	global_load_lds_dwordx4 v[246:247], off
	s_waitcnt vmcnt(6)
	s_barrier
	s_setprio 1
	v_mfma_f32_16x16x32_bf16 v[48:51], v[224:227], v[188:191], v[48:51]
	v_mfma_f32_16x16x32_bf16 v[44:47], v[232:235], v[188:191], v[44:47]
	v_mfma_f32_16x16x32_bf16 v[32:35], v[224:227], v[196:199], v[32:35]
	v_mfma_f32_16x16x32_bf16 v[28:31], v[232:235], v[196:199], v[28:31]
	v_mfma_f32_16x16x32_bf16 v[16:19], v[224:227], v[208:211], v[16:19]
	v_mfma_f32_16x16x32_bf16 v[12:15], v[232:235], v[208:211], v[12:15]
	v_mfma_f32_16x16x32_bf16 v[8:11], v[224:227], v[216:219], v[8:11]
	v_mfma_f32_16x16x32_bf16 v[4:7], v[232:235], v[216:219], v[4:7]
	v_mfma_f32_16x16x32_bf16 v[48:51], v[228:231], v[192:195], v[48:51]
	v_mfma_f32_16x16x32_bf16 v[44:47], v[236:239], v[192:195], v[44:47]
	v_mfma_f32_16x16x32_bf16 v[32:35], v[228:231], v[200:203], v[32:35]
	v_mfma_f32_16x16x32_bf16 v[28:31], v[236:239], v[200:203], v[28:31]
	v_mfma_f32_16x16x32_bf16 v[16:19], v[228:231], v[212:215], v[16:19]
	v_mfma_f32_16x16x32_bf16 v[12:15], v[236:239], v[212:215], v[12:15]
	s_setprio 2
	s_barrier
	v_mfma_f32_16x16x32_bf16 v[8:11], v[228:231], v[220:223], v[8:11]
	v_mfma_f32_16x16x32_bf16 v[4:7], v[236:239], v[220:223], v[4:7]
	s_setprio 0
	s_add_i32 s67, 0, 0x18000
	s_add_u32 s46, s46, 0x80000
	s_addc_u32 s47, s47, 0
	s_mov_b32 m0, s57
	v_lshl_add_u64 v[224:225], s[46:47], 0, v[138:139]
	ds_read_b128 v[188:191], v154 offset:32768
	ds_read_b128 v[192:195], v154 offset:33792
	ds_read_b128 v[196:199], v154 offset:34816
	ds_read_b128 v[200:203], v154 offset:35840
	ds_read_b128 v[208:211], v154 offset:36864
	ds_read_b128 v[212:215], v154 offset:37888
	ds_read_b128 v[216:219], v154 offset:38912
	ds_read_b128 v[220:223], v154 offset:39936
	global_load_lds_dwordx4 v[224:225], off
	v_lshl_add_u64 v[224:225], s[46:47], 0, v[134:135]
	s_mov_b32 m0, s58
	s_nop 0
	global_load_lds_dwordx4 v[224:225], off
	s_waitcnt lgkmcnt(8)
	s_barrier
	s_waitcnt lgkmcnt(0)
	s_setprio 1
	s_waitcnt lgkmcnt(0)
	v_mfma_f32_16x16x32_bf16 v[128:131], v[156:159], v[188:191], v[128:131]
	v_mfma_f32_16x16x32_bf16 v[124:127], v[180:183], v[188:191], v[124:127]
	v_mfma_f32_16x16x32_bf16 v[120:123], v[156:159], v[196:199], v[120:123]
	v_mfma_f32_16x16x32_bf16 v[116:119], v[180:183], v[196:199], v[116:119]
	v_mfma_f32_16x16x32_bf16 v[104:107], v[156:159], v[208:211], v[104:107]
	v_mfma_f32_16x16x32_bf16 v[100:103], v[180:183], v[208:211], v[100:103]
	v_mfma_f32_16x16x32_bf16 v[88:91], v[156:159], v[216:219], v[88:91]
	v_mfma_f32_16x16x32_bf16 v[84:87], v[180:183], v[216:219], v[84:87]
	v_mfma_f32_16x16x32_bf16 v[128:131], v[160:163], v[192:195], v[128:131]
	v_mfma_f32_16x16x32_bf16 v[124:127], v[184:187], v[192:195], v[124:127]
	v_mfma_f32_16x16x32_bf16 v[120:123], v[160:163], v[200:203], v[120:123]
	v_mfma_f32_16x16x32_bf16 v[116:119], v[184:187], v[200:203], v[116:119]
	v_mfma_f32_16x16x32_bf16 v[104:107], v[160:163], v[212:215], v[104:107]
	v_mfma_f32_16x16x32_bf16 v[100:103], v[184:187], v[212:215], v[100:103]
	s_setprio 2
	s_barrier
	v_mfma_f32_16x16x32_bf16 v[88:91], v[160:163], v[220:223], v[88:91]
	v_mfma_f32_16x16x32_bf16 v[84:87], v[184:187], v[220:223], v[84:87]
	s_setprio 0
	s_add_i32 s46, 0, 0x1c000
	s_add_i32 s47, s67, s54
	v_lshl_add_u64 v[148:149], v[148:149], 0, s[84:85]
	s_mov_b32 m0, s47
	ds_read_b128 v[224:227], v248 offset:49152
	ds_read_b128 v[228:231], v248 offset:50176
	ds_read_b128 v[232:235], v248 offset:51200
	ds_read_b128 v[236:239], v248 offset:52224
	global_load_lds_dwordx4 v[148:149], off
	v_lshl_add_u64 v[148:149], v[240:241], 0, s[84:85]
	s_add_i32 m0, s47, 0x2000
	s_nop 0
	global_load_lds_dwordx4 v[148:149], off
	s_barrier
	s_waitcnt lgkmcnt(0)
	s_setprio 1
	s_waitcnt lgkmcnt(0)
	v_mfma_f32_16x16x32_bf16 v[112:115], v[224:227], v[188:191], v[112:115]
	v_mfma_f32_16x16x32_bf16 v[108:111], v[232:235], v[188:191], v[108:111]
	v_mfma_f32_16x16x32_bf16 v[96:99], v[224:227], v[196:199], v[96:99]
	v_mfma_f32_16x16x32_bf16 v[92:95], v[232:235], v[196:199], v[92:95]
	v_mfma_f32_16x16x32_bf16 v[80:83], v[224:227], v[208:211], v[80:83]
	v_mfma_f32_16x16x32_bf16 v[76:79], v[232:235], v[208:211], v[76:79]
	v_mfma_f32_16x16x32_bf16 v[72:75], v[224:227], v[216:219], v[72:75]
	v_mfma_f32_16x16x32_bf16 v[68:71], v[232:235], v[216:219], v[68:71]
	v_mfma_f32_16x16x32_bf16 v[112:115], v[228:231], v[192:195], v[112:115]
	v_mfma_f32_16x16x32_bf16 v[108:111], v[236:239], v[192:195], v[108:111]
	v_mfma_f32_16x16x32_bf16 v[96:99], v[228:231], v[200:203], v[96:99]
	v_mfma_f32_16x16x32_bf16 v[92:95], v[236:239], v[200:203], v[92:95]
	v_mfma_f32_16x16x32_bf16 v[80:83], v[228:231], v[212:215], v[80:83]
	v_mfma_f32_16x16x32_bf16 v[76:79], v[236:239], v[212:215], v[76:79]
	s_setprio 2
	s_barrier
; #define PG8_STAGE(bufoff, gbase, voff) do { _Pragma("unroll") for (int _i = 0; _i < 2; ++_i) \
;     __builtin_amdgcn_global_load_lds((const unsigned*)((const char*)(gbase) + (voff)[_i]), (LAS unsigned*)(lds + (bufoff) + ldsw + _i * 8192), 16, 0, 0); } while (0)
; #define PG8_LDA(dst, b, h) do { _Pragma("unroll") for (int m = 0; m < 4; ++m) _Pragma("unroll") for (int k = 0; k < 2; ++k) dst[m][k] = *(const LAS bf16x8*)(lds + PG8_SA(b, h) + aoff + m * 2048 + k * 1024); } while (0)
; #define PG8_MMA(ai, bj, At, Bt) do { __builtin_amdgcn_s_setprio(1); _Pragma("unroll") for (int m = 0; m < 4; ++m) _Pragma("unroll") for (int n = 0; n < 2; ++n) _Pragma("unroll") for (int k = 0; k < 2; ++k) \
;     acc[ai][bj][m][n] = __builtin_amdgcn_mfma_f32_16x16x32_bf16(Bt[n][k], At[m][k], acc[ai][bj][m][n], 0, 0, 0); __builtin_amdgcn_s_setprio(0); } while (0)
; #define PG8_WAIT_V(n) asm volatile("s_waitcnt vmcnt(" #n ")" ::: "memory")
; #define PG8_WAIT_L(n) asm volatile("s_waitcnt lgkmcnt(" #n ")" ::: "memory")
; #define PG8_BAR __builtin_amdgcn_s_barrier()
; #define PG8_SCHED __builtin_amdgcn_sched_barrier(0)
; template <class Epi>
; DI void gemm_phase(LAS unsigned char* lds, const Gemm g, const Epi& E) {
;     ...
;       PG8_BAR; PG8_WAIT_L(0); PG8_MMA(0, 1, At, B1); PG8_BAR;
;       PG8_LDA(At, 1, 1); PG8_STAGE(PG8_SA(1, 0), a3, voffA);
;       PG8_BAR; PG8_WAIT_L(0); PG8_MMA(1, 0, At, B0); PG8_BAR; PG8_SCHED;
;       PG8_STAGE(PG8_SB(1, 1), b3 + hstepB, voffB);
;       PG8_WAIT_V(6); PG8_BAR; PG8_MMA(1, 1, At, B1); PG8_BAR;
;   DI void operator()(const f32x4 (&acc)[2][2][4][2], const Unit& u, int wr, int wc, int fr, int fq) const {
;     ...
;     } else {
;       if (wc == 0) {
; #pragma unroll
;         for (int ai = 0; ai < 2; ++ai)
; #pragma unroll
;           for (int m = 0; m < 4; ++m) {
;             float* zp = Z + (size_t)(row0 + ai * HALF + m * 16) * 32 + 8 * fq;
;             *(f32x4*)(zp) = acc[ai][0][m][0]; *(f32x4*)(zp + 4) = acc[ai][0][m][1];
;           }
;       }
	v_mfma_f32_16x16x32_bf16 v[72:75], v[228:231], v[220:223], v[72:75]
	v_mfma_f32_16x16x32_bf16 v[68:71], v[236:239], v[220:223], v[68:71]
	s_setprio 0
	s_mov_b32 m0, s60
	v_lshl_add_u64 v[148:149], v[242:243], 0, s[84:85]
	ds_read_b128 v[188:191], v154 offset:49152
	ds_read_b128 v[192:195], v154 offset:50176
	ds_read_b128 v[196:199], v154 offset:51200
	ds_read_b128 v[200:203], v154 offset:52224
	ds_read_b128 v[208:211], v154 offset:53248
	ds_read_b128 v[212:215], v154 offset:54272
	ds_read_b128 v[216:219], v154 offset:55296
	ds_read_b128 v[220:223], v154 offset:56320
	global_load_lds_dwordx4 v[148:149], off
	v_lshl_add_u64 v[148:149], v[244:245], 0, s[84:85]
	s_mov_b32 m0, s61
	s_nop 0
	global_load_lds_dwordx4 v[148:149], off
	s_waitcnt vmcnt(10)
	s_barrier
	s_waitcnt lgkmcnt(0)
	s_setprio 1
	s_waitcnt lgkmcnt(0)
	v_mfma_f32_16x16x32_bf16 v[64:67], v[156:159], v[188:191], v[64:67]
	v_mfma_f32_16x16x32_bf16 v[60:63], v[180:183], v[188:191], v[60:63]
	v_mfma_f32_16x16x32_bf16 v[56:59], v[156:159], v[196:199], v[56:59]
	v_mfma_f32_16x16x32_bf16 v[52:55], v[180:183], v[196:199], v[52:55]
	v_mfma_f32_16x16x32_bf16 v[40:43], v[156:159], v[208:211], v[40:43]
	v_mfma_f32_16x16x32_bf16 v[36:39], v[180:183], v[208:211], v[36:39]
	v_mfma_f32_16x16x32_bf16 v[24:27], v[156:159], v[216:219], v[24:27]
	v_mfma_f32_16x16x32_bf16 v[20:23], v[180:183], v[216:219], v[20:23]
	v_mfma_f32_16x16x32_bf16 v[64:67], v[160:163], v[192:195], v[64:67]
	v_mfma_f32_16x16x32_bf16 v[60:63], v[184:187], v[192:195], v[60:63]
	v_mfma_f32_16x16x32_bf16 v[56:59], v[160:163], v[200:203], v[56:59]
	v_mfma_f32_16x16x32_bf16 v[52:55], v[184:187], v[200:203], v[52:55]
	v_mfma_f32_16x16x32_bf16 v[40:43], v[160:163], v[212:215], v[40:43]
	v_mfma_f32_16x16x32_bf16 v[36:39], v[184:187], v[212:215], v[36:39]
	s_setprio 2
	s_barrier
	v_mfma_f32_16x16x32_bf16 v[24:27], v[160:163], v[220:223], v[24:27]
	v_mfma_f32_16x16x32_bf16 v[20:23], v[184:187], v[220:223], v[20:23]
	s_setprio 0
	ds_read_b128 v[156:159], v248
	ds_read_b128 v[160:163], v248 offset:1024
	ds_read_b128 v[180:183], v248 offset:2048
	ds_read_b128 v[184:187], v248 offset:3072
	s_add_u32 s44, s44, 0x80080
	s_addc_u32 s45, s45, 0
	s_add_i32 s46, s46, s54
	v_lshl_add_u64 v[148:149], s[44:45], 0, v[136:137]
	s_mov_b32 m0, s46
	s_nop 0
	global_load_lds_dwordx4 v[148:149], off
	v_lshl_add_u64 v[148:149], s[44:45], 0, v[132:133]
	s_add_i32 m0, s46, 0x2000
	s_nop 0
	global_load_lds_dwordx4 v[148:149], off
	s_waitcnt vmcnt(6)
	s_barrier
	s_setprio 1
	v_mfma_f32_16x16x32_bf16 v[48:51], v[224:227], v[188:191], v[48:51]
	v_mfma_f32_16x16x32_bf16 v[44:47], v[232:235], v[188:191], v[44:47]
	v_mfma_f32_16x16x32_bf16 v[32:35], v[224:227], v[196:199], v[32:35]
	v_mfma_f32_16x16x32_bf16 v[28:31], v[232:235], v[196:199], v[28:31]
	v_mfma_f32_16x16x32_bf16 v[16:19], v[224:227], v[208:211], v[16:19]
	v_mfma_f32_16x16x32_bf16 v[12:15], v[232:235], v[208:211], v[12:15]
	v_mfma_f32_16x16x32_bf16 v[8:11], v[224:227], v[216:219], v[8:11]
	v_mfma_f32_16x16x32_bf16 v[4:7], v[232:235], v[216:219], v[4:7]
	v_mfma_f32_16x16x32_bf16 v[48:51], v[228:231], v[192:195], v[48:51]
	v_mfma_f32_16x16x32_bf16 v[44:47], v[236:239], v[192:195], v[44:47]
	v_mfma_f32_16x16x32_bf16 v[32:35], v[228:231], v[200:203], v[32:35]
	v_mfma_f32_16x16x32_bf16 v[28:31], v[236:239], v[200:203], v[28:31]
	v_mfma_f32_16x16x32_bf16 v[16:19], v[228:231], v[212:215], v[16:19]
	v_mfma_f32_16x16x32_bf16 v[12:15], v[236:239], v[212:215], v[12:15]
	s_setprio 2
	s_barrier
	v_mfma_f32_16x16x32_bf16 v[8:11], v[228:231], v[220:223], v[8:11]
	v_mfma_f32_16x16x32_bf16 v[4:7], v[236:239], v[220:223], v[4:7]
	s_setprio 0
	s_add_i32 s66, s66, 2
	s_add_u32 s42, s42, 0x100
	s_addc_u32 s43, s43, 0
	s_add_u32 s64, s64, 0x100
	s_addc_u32 s65, s65, 0
	s_cmp_gt_u32 s66, 29
	s_cbranch_scc0 .LBB0_225
	s_waitcnt lgkmcnt(0)
	s_lshl_b32 s23, s40, 8
	s_add_i32 s23, s23, s59
	s_cmp_gt_i32 s62, 7
	s_cselect_b64 s[40:41], -1, 0
	s_and_b32 s27, s62, 0x7ffffff8
	s_cmp_lg_u32 s27, 16
	s_cselect_b64 s[42:43], -1, 0
	s_and_b64 s[44:45], s[40:41], s[42:43]
	v_or_b32_e32 v148, s23, v150
	s_mov_b64 s[42:43], -1
	s_and_b64 vcc, exec, s[44:45]
	s_cbranch_vccz .LBB0_234
	s_cmp_gt_u32 s62, 15
	s_cbranch_scc0 .LBB0_231
	s_andn2_b64 vcc, exec, s[18:19]
	s_cbranch_vccnz .LBB0_230
	v_or_b32_e32 v158, 16, v148
	v_ashrrev_i32_e32 v149, 31, v148
	v_ashrrev_i32_e32 v159, 31, v158
	v_lshlrev_b64 v[156:157], 7, v[148:149]
	v_lshlrev_b64 v[158:159], 7, v[158:159]
	v_lshl_add_u64 v[156:157], v[140:141], 0, v[156:157]
	v_lshl_add_u64 v[158:159], v[140:141], 0, v[158:159]
	global_store_dwordx4 v[156:157], v[128:131], off
	global_store_dwordx4 v[156:157], v[124:127], off offset:16
	global_store_dwordx4 v[158:159], v[120:123], off
	global_store_dwordx4 v[158:159], v[116:119], off offset:16
	v_or_b32_e32 v158, 32, v148
	v_ashrrev_i32_e32 v159, 31, v158
	v_lshlrev_b64 v[158:159], 7, v[158:159]
	v_lshl_add_u64 v[158:159], v[140:141], 0, v[158:159]
	global_store_dwordx4 v[158:159], v[104:107], off
	global_store_dwordx4 v[158:159], v[100:103], off offset:16
	v_or_b32_e32 v158, 48, v148
	v_ashrrev_i32_e32 v159, 31, v158
	v_lshlrev_b64 v[158:159], 7, v[158:159]
	s_movk_i32 s27, 0x4000
	v_lshl_add_u64 v[158:159], v[140:141], 0, v[158:159]
	s_mov_b64 s[42:43], 0x4000
	v_add_co_u32_e32 v160, vcc, s27, v156
	global_store_dwordx4 v[158:159], v[88:91], off
	global_store_dwordx4 v[158:159], v[84:87], off offset:16
	v_lshl_add_u64 v[158:159], v[156:157], 0, s[42:43]
	v_addc_co_u32_e32 v161, vcc, 0, v157, vcc
	s_mov_b64 s[42:43], 0x4800
	global_store_dwordx4 v[160:161], v[64:67], off
	global_store_dwordx4 v[158:159], v[60:63], off offset:16
	v_lshl_add_u64 v[158:159], v[156:157], 0, s[42:43]
	global_store_dwordx4 v[160:161], v[56:59], off offset:2048
	global_store_dwordx4 v[158:159], v[52:55], off offset:16
	s_mov_b64 s[42:43], 0x5000
	v_add_co_u32_e32 v160, vcc, 0x5000, v156
	v_lshl_add_u64 v[158:159], v[156:157], 0, s[42:43]
	s_nop 0
	v_addc_co_u32_e32 v161, vcc, 0, v157, vcc
	s_mov_b64 s[42:43], 0x5800
	global_store_dwordx4 v[160:161], v[40:43], off
	global_store_dwordx4 v[158:159], v[36:39], off offset:16
	v_lshl_add_u64 v[156:157], v[156:157], 0, s[42:43]
	global_store_dwordx4 v[160:161], v[24:27], off offset:2048
	global_store_dwordx4 v[156:157], v[20:23], off offset:16

; #define PG8_STAGE(bufoff, gbase, voff) do { _Pragma("unroll") for (int _i = 0; _i < 2; ++_i) \
;     __builtin_amdgcn_global_load_lds((const unsigned*)((const char*)(gbase) + (voff)[_i]), (LAS unsigned*)(lds + (bufoff) + ldsw + _i * 8192), 16, 0, 0); } while (0)
; #define PG8_LDA(dst, b, h) do { _Pragma("unroll") for (int m = 0; m < 4; ++m) _Pragma("unroll") for (int k = 0; k < 2; ++k) dst[m][k] = *(const LAS bf16x8*)(lds + PG8_SA(b, h) + aoff + m * 2048 + k * 1024); } while (0)
; #define PG8_LDB(dst, b, h) do { _Pragma("unroll") for (int n = 0; n < 2; ++n) _Pragma("unroll") for (int k = 0; k < 2; ++k) dst[n][k] = *(const LAS bf16x8*)(lds + PG8_SB(b, h) + boff + n * 2048 + k * 1024); } while (0)
; #define PG8_MMA(ai, bj, At, Bt) do { __builtin_amdgcn_s_setprio(1); _Pragma("unroll") for (int m = 0; m < 4; ++m) _Pragma("unroll") for (int n = 0; n < 2; ++n) _Pragma("unroll") for (int k = 0; k < 2; ++k) \
;     acc[ai][bj][m][n] = __builtin_amdgcn_mfma_f32_16x16x32_bf16(Bt[n][k], At[m][k], acc[ai][bj][m][n], 0, 0, 0); __builtin_amdgcn_s_setprio(0); } while (0)
; #define PG8_WAIT_V(n) asm volatile("s_waitcnt vmcnt(" #n ")" ::: "memory")
; #define PG8_BAR __builtin_amdgcn_s_barrier()
; template <class Epi>
; DI void gemm_phase(LAS unsigned char* lds, const Gemm g, const Epi& E) {
;     ...
;     for (int t = 0; t < nt; t += 2) {
;       const bool last = (t == nt - 2);
;       const char* a1 = cA + (size_t)(t + 1) * kstep;
;       const char* a2 = last ? nA : cA + (size_t)(t + 2) * kstep; const char* b2 = last ? nB : cB + (size_t)(t + 2) * kstep;
;       const char* a3 = a2 + kstep; const char* b3 = b2 + kstep;
;       PG8_LDB(B0, 0, 0); PG8_SCHED; PG8_LDA(At, 0, 0); PG8_STAGE(PG8_SA(1, 1), a1 + hstepA, voffA);
;       PG8_WAIT_L(8); PG8_BAR; PG8_WAIT_L(0); PG8_MMA(0, 0, At, B0); PG8_BAR; PG8_SCHED;
;       PG8_LDB(B1, 0, 1); PG8_STAGE(PG8_SB(0, 0), b2, voffB);
;       PG8_BAR; PG8_WAIT_L(0); PG8_MMA(0, 1, At, B1); PG8_BAR;
;       PG8_LDA(At, 0, 1); PG8_STAGE(PG8_SA(0, 0), a2, voffA);
;       PG8_BAR; PG8_WAIT_L(0); PG8_MMA(1, 0, At, B0); PG8_BAR; PG8_SCHED;
;       PG8_STAGE(PG8_SB(0, 1), b2 + hstepB, voffB);
;       PG8_WAIT_V(6); PG8_BAR; PG8_MMA(1, 1, At, B1); PG8_BAR;
;       PG8_LDB(B0, 1, 0); PG8_SCHED; PG8_LDA(At, 1, 0); PG8_STAGE(PG8_SA(0, 1), a2 + hstepA, voffA);
;       PG8_WAIT_L(8); PG8_BAR; PG8_WAIT_L(0); PG8_MMA(0, 0, At, B0); PG8_BAR; PG8_SCHED;
.LBB0_514:
	s_add_i32 s78, s44, 2
	s_add_u32 s56, s42, 0x80
	s_addc_u32 s45, s43, 0
	s_add_i32 s79, 0, 0x10000
	s_cmp_eq_u32 s72, s44
	s_cselect_b32 s44, s52, s56
	s_cselect_b32 s45, s53, s45
	s_cselect_b32 s57, s55, s59
	s_cselect_b32 s56, s54, s58
	v_lshl_add_u64 v[190:191], s[42:43], 0, v[186:187]
	s_add_i32 m0, s64, 0xc000
	ds_read_b128 v[148:151], v195
	ds_read_b128 v[152:155], v195 offset:1024
	ds_read_b128 v[156:159], v195 offset:2048
	ds_read_b128 v[160:163], v195 offset:3072
	ds_read_b128 v[196:199], v195 offset:4096
	ds_read_b128 v[200:203], v195 offset:5120
	ds_read_b128 v[208:211], v195 offset:6144
	ds_read_b128 v[212:215], v195 offset:7168
	global_load_lds_dwordx4 v[190:191], off
	v_lshl_add_u64 v[190:191], s[42:43], 0, v[188:189]
	s_add_i32 m0, s64, 0xe000
	s_nop 0
	global_load_lds_dwordx4 v[190:191], off
	s_waitcnt lgkmcnt(8)
	s_barrier
	s_waitcnt lgkmcnt(0)
	s_setprio 1
	s_waitcnt lgkmcnt(0)
	v_mfma_f32_16x16x32_bf16 v[128:131], v[132:135], v[148:151], v[128:131]
	v_mfma_f32_16x16x32_bf16 v[124:127], v[140:143], v[148:151], v[124:127]
	v_mfma_f32_16x16x32_bf16 v[116:119], v[132:135], v[156:159], v[116:119]
	v_mfma_f32_16x16x32_bf16 v[108:111], v[140:143], v[156:159], v[108:111]
	v_mfma_f32_16x16x32_bf16 v[100:103], v[132:135], v[196:199], v[100:103]
	v_mfma_f32_16x16x32_bf16 v[92:95], v[140:143], v[196:199], v[92:95]
	v_mfma_f32_16x16x32_bf16 v[84:87], v[132:135], v[208:211], v[84:87]
	v_mfma_f32_16x16x32_bf16 v[76:79], v[140:143], v[208:211], v[76:79]
	v_mfma_f32_16x16x32_bf16 v[128:131], v[136:139], v[152:155], v[128:131]
	v_mfma_f32_16x16x32_bf16 v[124:127], v[144:147], v[152:155], v[124:127]
	v_mfma_f32_16x16x32_bf16 v[116:119], v[136:139], v[160:163], v[116:119]
	v_mfma_f32_16x16x32_bf16 v[108:111], v[144:147], v[160:163], v[108:111]
	v_mfma_f32_16x16x32_bf16 v[100:103], v[136:139], v[200:203], v[100:103]
	v_mfma_f32_16x16x32_bf16 v[92:95], v[144:147], v[200:203], v[92:95]
	s_setprio 2
	s_barrier
	v_mfma_f32_16x16x32_bf16 v[84:87], v[136:139], v[212:215], v[84:87]
	v_mfma_f32_16x16x32_bf16 v[76:79], v[144:147], v[212:215], v[76:79]
	s_setprio 0
	s_add_i32 s80, 0, 0x14000
	s_add_i32 s79, s79, s63
	ds_read_b128 v[216:219], v248 offset:16384
	ds_read_b128 v[220:223], v248 offset:17408
	ds_read_b128 v[224:227], v248 offset:18432
	ds_read_b128 v[228:231], v248 offset:19456
	v_lshl_add_u64 v[190:191], s[56:57], 0, v[2:3]
	s_mov_b32 m0, s79
	v_lshl_add_u64 v[232:233], s[56:57], 0, v[184:185]
	global_load_lds_dwordx4 v[190:191], off
	s_add_i32 m0, s79, 0x2000
	s_nop 0
	global_load_lds_dwordx4 v[232:233], off
	s_barrier
	s_waitcnt lgkmcnt(0)
	s_setprio 1
	s_waitcnt lgkmcnt(0)
	v_mfma_f32_16x16x32_bf16 v[120:123], v[216:219], v[148:151], v[120:123]
	v_mfma_f32_16x16x32_bf16 v[112:115], v[224:227], v[148:151], v[112:115]
	v_mfma_f32_16x16x32_bf16 v[104:107], v[216:219], v[156:159], v[104:107]
	v_mfma_f32_16x16x32_bf16 v[96:99], v[224:227], v[156:159], v[96:99]
	v_mfma_f32_16x16x32_bf16 v[88:91], v[216:219], v[196:199], v[88:91]
	v_mfma_f32_16x16x32_bf16 v[80:83], v[224:227], v[196:199], v[80:83]
	v_mfma_f32_16x16x32_bf16 v[72:75], v[216:219], v[208:211], v[72:75]
	v_mfma_f32_16x16x32_bf16 v[68:71], v[224:227], v[208:211], v[68:71]
	v_mfma_f32_16x16x32_bf16 v[120:123], v[220:223], v[152:155], v[120:123]
	v_mfma_f32_16x16x32_bf16 v[112:115], v[228:231], v[152:155], v[112:115]
	v_mfma_f32_16x16x32_bf16 v[104:107], v[220:223], v[160:163], v[104:107]
	v_mfma_f32_16x16x32_bf16 v[96:99], v[228:231], v[160:163], v[96:99]
	v_mfma_f32_16x16x32_bf16 v[88:91], v[220:223], v[200:203], v[88:91]
	v_mfma_f32_16x16x32_bf16 v[80:83], v[228:231], v[200:203], v[80:83]
	s_setprio 2
	s_barrier
	v_mfma_f32_16x16x32_bf16 v[72:75], v[220:223], v[212:215], v[72:75]
	v_mfma_f32_16x16x32_bf16 v[68:71], v[228:231], v[212:215], v[68:71]
	s_setprio 0
	s_mov_b32 m0, s64
	v_lshl_add_u64 v[234:235], s[44:45], 0, v[180:181]
	ds_read_b128 v[148:151], v195 offset:16384
	ds_read_b128 v[152:155], v195 offset:17408
	ds_read_b128 v[156:159], v195 offset:18432
	ds_read_b128 v[160:163], v195 offset:19456
	ds_read_b128 v[196:199], v195 offset:20480
	ds_read_b128 v[200:203], v195 offset:21504
	ds_read_b128 v[208:211], v195 offset:22528
	ds_read_b128 v[212:215], v195 offset:23552
	global_load_lds_dwordx4 v[234:235], off
	v_lshl_add_u64 v[236:237], s[44:45], 0, v[182:183]
	s_mov_b32 m0, s65
	s_nop 0
	global_load_lds_dwordx4 v[236:237], off
	s_waitcnt vmcnt(10)
	s_barrier
	s_waitcnt lgkmcnt(0)
	s_setprio 1
	s_waitcnt lgkmcnt(0)
	v_mfma_f32_16x16x32_bf16 v[64:67], v[132:135], v[148:151], v[64:67]
	v_mfma_f32_16x16x32_bf16 v[60:63], v[140:143], v[148:151], v[60:63]
	v_mfma_f32_16x16x32_bf16 v[56:59], v[132:135], v[156:159], v[56:59]
	v_mfma_f32_16x16x32_bf16 v[48:51], v[140:143], v[156:159], v[48:51]
	v_mfma_f32_16x16x32_bf16 v[40:43], v[132:135], v[196:199], v[40:43]
	v_mfma_f32_16x16x32_bf16 v[32:35], v[140:143], v[196:199], v[32:35]
	v_mfma_f32_16x16x32_bf16 v[24:27], v[132:135], v[208:211], v[24:27]
	v_mfma_f32_16x16x32_bf16 v[16:19], v[140:143], v[208:211], v[16:19]
	v_mfma_f32_16x16x32_bf16 v[64:67], v[136:139], v[152:155], v[64:67]
	v_mfma_f32_16x16x32_bf16 v[60:63], v[144:147], v[152:155], v[60:63]
	v_mfma_f32_16x16x32_bf16 v[56:59], v[136:139], v[160:163], v[56:59]
	v_mfma_f32_16x16x32_bf16 v[48:51], v[144:147], v[160:163], v[48:51]
	v_mfma_f32_16x16x32_bf16 v[40:43], v[136:139], v[200:203], v[40:43]
	v_mfma_f32_16x16x32_bf16 v[32:35], v[144:147], v[200:203], v[32:35]
	s_setprio 2
	s_barrier
; #define PG8_STAGE(bufoff, gbase, voff) do { _Pragma("unroll") for (int _i = 0; _i < 2; ++_i) \
;     __builtin_amdgcn_global_load_lds((const unsigned*)((const char*)(gbase) + (voff)[_i]), (LAS unsigned*)(lds + (bufoff) + ldsw + _i * 8192), 16, 0, 0); } while (0)
; #define PG8_LDA(dst, b, h) do { _Pragma("unroll") for (int m = 0; m < 4; ++m) _Pragma("unroll") for (int k = 0; k < 2; ++k) dst[m][k] = *(const LAS bf16x8*)(lds + PG8_SA(b, h) + aoff + m * 2048 + k * 1024); } while (0)
; #define PG8_LDB(dst, b, h) do { _Pragma("unroll") for (int n = 0; n < 2; ++n) _Pragma("unroll") for (int k = 0; k < 2; ++k) dst[n][k] = *(const LAS bf16x8*)(lds + PG8_SB(b, h) + boff + n * 2048 + k * 1024); } while (0)
; #define PG8_MMA(ai, bj, At, Bt) do { __builtin_amdgcn_s_setprio(1); _Pragma("unroll") for (int m = 0; m < 4; ++m) _Pragma("unroll") for (int n = 0; n < 2; ++n) _Pragma("unroll") for (int k = 0; k < 2; ++k) \
;     acc[ai][bj][m][n] = __builtin_amdgcn_mfma_f32_16x16x32_bf16(Bt[n][k], At[m][k], acc[ai][bj][m][n], 0, 0, 0); __builtin_amdgcn_s_setprio(0); } while (0)
; #define PG8_WAIT_V(n) asm volatile("s_waitcnt vmcnt(" #n ")" ::: "memory")
; #define PG8_WAIT_L(n) asm volatile("s_waitcnt lgkmcnt(" #n ")" ::: "memory")
; #define PG8_BAR __builtin_amdgcn_s_barrier()
; #define PG8_SCHED __builtin_amdgcn_sched_barrier(0)
; template <class Epi>
; DI void gemm_phase(LAS unsigned char* lds, const Gemm g, const Epi& E) {
;     ...
;       PG8_WAIT_V(6); PG8_BAR; PG8_MMA(1, 1, At, B1); PG8_BAR;
;       PG8_LDB(B0, 1, 0); PG8_SCHED; PG8_LDA(At, 1, 0); PG8_STAGE(PG8_SA(0, 1), a2 + hstepA, voffA);
;       PG8_WAIT_L(8); PG8_BAR; PG8_WAIT_L(0); PG8_MMA(0, 0, At, B0); PG8_BAR; PG8_SCHED;
;       PG8_LDB(B1, 1, 1); PG8_STAGE(PG8_SB(1, 0), b3, voffB);
;       PG8_BAR; PG8_WAIT_L(0); PG8_MMA(0, 1, At, B1); PG8_BAR;
;       PG8_LDA(At, 1, 1); PG8_STAGE(PG8_SA(1, 0), a3, voffA);
;       PG8_BAR; PG8_WAIT_L(0); PG8_MMA(1, 0, At, B0); PG8_BAR; PG8_SCHED;
	v_mfma_f32_16x16x32_bf16 v[24:27], v[136:139], v[212:215], v[24:27]
	v_mfma_f32_16x16x32_bf16 v[16:19], v[144:147], v[212:215], v[16:19]
	s_setprio 0
	ds_read_b128 v[132:135], v248 offset:32768
	ds_read_b128 v[136:139], v248 offset:33792
	ds_read_b128 v[140:143], v248 offset:34816
	ds_read_b128 v[144:147], v248 offset:35840
	s_add_u32 s56, s56, s18
	s_addc_u32 s57, s57, s19
	s_add_i32 s79, s80, s63
	v_lshl_add_u64 v[238:239], s[56:57], 0, v[2:3]
	s_mov_b32 m0, s79
	v_lshl_add_u64 v[240:241], s[56:57], 0, v[184:185]
	global_load_lds_dwordx4 v[238:239], off
	s_add_i32 m0, s79, 0x2000
	s_nop 0
	global_load_lds_dwordx4 v[240:241], off
	s_waitcnt vmcnt(6)
	s_barrier
	s_setprio 1
	v_mfma_f32_16x16x32_bf16 v[52:55], v[216:219], v[148:151], v[52:55]
	v_mfma_f32_16x16x32_bf16 v[44:47], v[224:227], v[148:151], v[44:47]
	v_mfma_f32_16x16x32_bf16 v[36:39], v[216:219], v[156:159], v[36:39]
	v_mfma_f32_16x16x32_bf16 v[28:31], v[224:227], v[156:159], v[28:31]
	v_mfma_f32_16x16x32_bf16 v[20:23], v[216:219], v[196:199], v[20:23]
	v_mfma_f32_16x16x32_bf16 v[12:15], v[224:227], v[196:199], v[12:15]
	v_mfma_f32_16x16x32_bf16 v[8:11], v[216:219], v[208:211], v[8:11]
	v_mfma_f32_16x16x32_bf16 v[4:7], v[224:227], v[208:211], v[4:7]
	v_mfma_f32_16x16x32_bf16 v[52:55], v[220:223], v[152:155], v[52:55]
	v_mfma_f32_16x16x32_bf16 v[44:47], v[228:231], v[152:155], v[44:47]
	v_mfma_f32_16x16x32_bf16 v[36:39], v[220:223], v[160:163], v[36:39]
	v_mfma_f32_16x16x32_bf16 v[28:31], v[228:231], v[160:163], v[28:31]
	v_mfma_f32_16x16x32_bf16 v[20:23], v[220:223], v[200:203], v[20:23]
	v_mfma_f32_16x16x32_bf16 v[12:15], v[228:231], v[200:203], v[12:15]
	s_setprio 2
	s_barrier
	v_mfma_f32_16x16x32_bf16 v[8:11], v[220:223], v[212:215], v[8:11]
	v_mfma_f32_16x16x32_bf16 v[4:7], v[228:231], v[212:215], v[4:7]
	s_setprio 0
	s_add_i32 s56, 0, 0x18000
	s_add_u32 s44, s44, s8
	s_addc_u32 s45, s45, 0
	s_mov_b32 m0, s66
	v_lshl_add_u64 v[216:217], s[44:45], 0, v[180:181]
	ds_read_b128 v[148:151], v195 offset:32768
	ds_read_b128 v[152:155], v195 offset:33792
	ds_read_b128 v[156:159], v195 offset:34816
	ds_read_b128 v[160:163], v195 offset:35840
	ds_read_b128 v[196:199], v195 offset:36864
	ds_read_b128 v[200:203], v195 offset:37888
	ds_read_b128 v[208:211], v195 offset:38912
	ds_read_b128 v[212:215], v195 offset:39936
	global_load_lds_dwordx4 v[216:217], off
	v_lshl_add_u64 v[216:217], s[44:45], 0, v[182:183]
	s_mov_b32 m0, s67
	s_nop 0
	global_load_lds_dwordx4 v[216:217], off
	s_waitcnt lgkmcnt(8)
	s_barrier
	s_waitcnt lgkmcnt(0)
	s_setprio 1
	s_waitcnt lgkmcnt(0)
	v_mfma_f32_16x16x32_bf16 v[128:131], v[132:135], v[148:151], v[128:131]
	v_mfma_f32_16x16x32_bf16 v[124:127], v[140:143], v[148:151], v[124:127]
	v_mfma_f32_16x16x32_bf16 v[116:119], v[132:135], v[156:159], v[116:119]
	v_mfma_f32_16x16x32_bf16 v[108:111], v[140:143], v[156:159], v[108:111]
	v_mfma_f32_16x16x32_bf16 v[100:103], v[132:135], v[196:199], v[100:103]
	v_mfma_f32_16x16x32_bf16 v[92:95], v[140:143], v[196:199], v[92:95]
	v_mfma_f32_16x16x32_bf16 v[84:87], v[132:135], v[208:211], v[84:87]
	v_mfma_f32_16x16x32_bf16 v[76:79], v[140:143], v[208:211], v[76:79]
	v_mfma_f32_16x16x32_bf16 v[128:131], v[136:139], v[152:155], v[128:131]
	v_mfma_f32_16x16x32_bf16 v[124:127], v[144:147], v[152:155], v[124:127]
	v_mfma_f32_16x16x32_bf16 v[116:119], v[136:139], v[160:163], v[116:119]
	v_mfma_f32_16x16x32_bf16 v[108:111], v[144:147], v[160:163], v[108:111]
	v_mfma_f32_16x16x32_bf16 v[100:103], v[136:139], v[200:203], v[100:103]
	v_mfma_f32_16x16x32_bf16 v[92:95], v[144:147], v[200:203], v[92:95]
	s_setprio 2
	s_barrier
	v_mfma_f32_16x16x32_bf16 v[84:87], v[136:139], v[212:215], v[84:87]
	v_mfma_f32_16x16x32_bf16 v[76:79], v[144:147], v[212:215], v[76:79]
	s_setprio 0
	s_add_i32 s44, 0, 0x1c000
	s_add_i32 s45, s56, s63
	v_lshl_add_u64 v[190:191], v[190:191], 0, s[84:85]
	s_mov_b32 m0, s45
	ds_read_b128 v[216:219], v248 offset:49152
	ds_read_b128 v[220:223], v248 offset:50176
	ds_read_b128 v[224:227], v248 offset:51200
	ds_read_b128 v[228:231], v248 offset:52224
	global_load_lds_dwordx4 v[190:191], off
	v_lshl_add_u64 v[190:191], v[232:233], 0, s[84:85]
	s_add_i32 m0, s45, 0x2000
	s_nop 0
	global_load_lds_dwordx4 v[190:191], off
	s_barrier
; #define PG8_STAGE(bufoff, gbase, voff) do { _Pragma("unroll") for (int _i = 0; _i < 2; ++_i) \
;     __builtin_amdgcn_global_load_lds((const unsigned*)((const char*)(gbase) + (voff)[_i]), (LAS unsigned*)(lds + (bufoff) + ldsw + _i * 8192), 16, 0, 0); } while (0)
; #define PG8_LDA(dst, b, h) do { _Pragma("unroll") for (int m = 0; m < 4; ++m) _Pragma("unroll") for (int k = 0; k < 2; ++k) dst[m][k] = *(const LAS bf16x8*)(lds + PG8_SA(b, h) + aoff + m * 2048 + k * 1024); } while (0)
; #define PG8_MMA(ai, bj, At, Bt) do { __builtin_amdgcn_s_setprio(1); _Pragma("unroll") for (int m = 0; m < 4; ++m) _Pragma("unroll") for (int n = 0; n < 2; ++n) _Pragma("unroll") for (int k = 0; k < 2; ++k) \
;     acc[ai][bj][m][n] = __builtin_amdgcn_mfma_f32_16x16x32_bf16(Bt[n][k], At[m][k], acc[ai][bj][m][n], 0, 0, 0); __builtin_amdgcn_s_setprio(0); } while (0)
; #define PG8_WAIT_V(n) asm volatile("s_waitcnt vmcnt(" #n ")" ::: "memory")
; #define PG8_WAIT_L(n) asm volatile("s_waitcnt lgkmcnt(" #n ")" ::: "memory")
; #define PG8_BAR __builtin_amdgcn_s_barrier()
; #define PG8_SCHED __builtin_amdgcn_sched_barrier(0)
; template <class Epi>
; DI void gemm_phase(LAS unsigned char* lds, const Gemm g, const Epi& E) {
;     ...
;       PG8_BAR; PG8_WAIT_L(0); PG8_MMA(0, 1, At, B1); PG8_BAR;
;       PG8_LDA(At, 1, 1); PG8_STAGE(PG8_SA(1, 0), a3, voffA);
;       PG8_BAR; PG8_WAIT_L(0); PG8_MMA(1, 0, At, B0); PG8_BAR; PG8_SCHED;
;       PG8_STAGE(PG8_SB(1, 1), b3 + hstepB, voffB);
;       PG8_WAIT_V(6); PG8_BAR; PG8_MMA(1, 1, At, B1); PG8_BAR;
;   DI void operator()(const f32x4 (&acc)[2][2][4][2], const Unit& u, int wr, int wc, int fr, int fq) const {
;     const int row0 = u.pm * BM + wr * 64 + fr, col0 = u.pn * BM + wc * 32 + 8 * fq;
;     f32x4 bv[2][2], sv[2][2];
; #pragma unroll
;     for (int bj = 0; bj < 2; ++bj)
; #pragma unroll
;       for (int n = 0; n < 2; ++n) {
;         bv[bj][n] = bias ? *(const f32x4*)(bias + col0 + bj * HALF + 4 * n) : (f32x4){0.f, 0.f, 0.f, 0.f};
;         sv[bj][n] = scale ? *(const f32x4*)(scale + col0 + bj * HALF + 4 * n) : (f32x4){1.f, 1.f, 1.f, 1.f};
;       }
	s_waitcnt lgkmcnt(0)
	s_setprio 1
	s_waitcnt lgkmcnt(0)
	v_mfma_f32_16x16x32_bf16 v[120:123], v[216:219], v[148:151], v[120:123]
	v_mfma_f32_16x16x32_bf16 v[112:115], v[224:227], v[148:151], v[112:115]
	v_mfma_f32_16x16x32_bf16 v[104:107], v[216:219], v[156:159], v[104:107]
	v_mfma_f32_16x16x32_bf16 v[96:99], v[224:227], v[156:159], v[96:99]
	v_mfma_f32_16x16x32_bf16 v[88:91], v[216:219], v[196:199], v[88:91]
	v_mfma_f32_16x16x32_bf16 v[80:83], v[224:227], v[196:199], v[80:83]
	v_mfma_f32_16x16x32_bf16 v[72:75], v[216:219], v[208:211], v[72:75]
	v_mfma_f32_16x16x32_bf16 v[68:71], v[224:227], v[208:211], v[68:71]
	v_mfma_f32_16x16x32_bf16 v[120:123], v[220:223], v[152:155], v[120:123]
	v_mfma_f32_16x16x32_bf16 v[112:115], v[228:231], v[152:155], v[112:115]
	v_mfma_f32_16x16x32_bf16 v[104:107], v[220:223], v[160:163], v[104:107]
	v_mfma_f32_16x16x32_bf16 v[96:99], v[228:231], v[160:163], v[96:99]
	v_mfma_f32_16x16x32_bf16 v[88:91], v[220:223], v[200:203], v[88:91]
	v_mfma_f32_16x16x32_bf16 v[80:83], v[228:231], v[200:203], v[80:83]
	s_setprio 2
	s_barrier
	v_mfma_f32_16x16x32_bf16 v[72:75], v[220:223], v[212:215], v[72:75]
	v_mfma_f32_16x16x32_bf16 v[68:71], v[228:231], v[212:215], v[68:71]
	s_setprio 0
	s_mov_b32 m0, s69
	v_lshl_add_u64 v[190:191], v[234:235], 0, s[84:85]
	ds_read_b128 v[148:151], v195 offset:49152
	ds_read_b128 v[152:155], v195 offset:50176
	ds_read_b128 v[156:159], v195 offset:51200
	ds_read_b128 v[160:163], v195 offset:52224
	ds_read_b128 v[196:199], v195 offset:53248
	ds_read_b128 v[200:203], v195 offset:54272
	ds_read_b128 v[208:211], v195 offset:55296
	ds_read_b128 v[212:215], v195 offset:56320
	global_load_lds_dwordx4 v[190:191], off
	v_lshl_add_u64 v[190:191], v[236:237], 0, s[84:85]
	s_mov_b32 m0, s71
	s_nop 0
	global_load_lds_dwordx4 v[190:191], off
	s_waitcnt vmcnt(10)
	s_barrier
	s_waitcnt lgkmcnt(0)
	s_setprio 1
	s_waitcnt lgkmcnt(0)
	v_mfma_f32_16x16x32_bf16 v[64:67], v[132:135], v[148:151], v[64:67]
	v_mfma_f32_16x16x32_bf16 v[60:63], v[140:143], v[148:151], v[60:63]
	v_mfma_f32_16x16x32_bf16 v[56:59], v[132:135], v[156:159], v[56:59]
	v_mfma_f32_16x16x32_bf16 v[48:51], v[140:143], v[156:159], v[48:51]
	v_mfma_f32_16x16x32_bf16 v[40:43], v[132:135], v[196:199], v[40:43]
	v_mfma_f32_16x16x32_bf16 v[32:35], v[140:143], v[196:199], v[32:35]
	v_mfma_f32_16x16x32_bf16 v[24:27], v[132:135], v[208:211], v[24:27]
	v_mfma_f32_16x16x32_bf16 v[16:19], v[140:143], v[208:211], v[16:19]
	v_mfma_f32_16x16x32_bf16 v[64:67], v[136:139], v[152:155], v[64:67]
	v_mfma_f32_16x16x32_bf16 v[60:63], v[144:147], v[152:155], v[60:63]
	v_mfma_f32_16x16x32_bf16 v[56:59], v[136:139], v[160:163], v[56:59]
	v_mfma_f32_16x16x32_bf16 v[48:51], v[144:147], v[160:163], v[48:51]
	v_mfma_f32_16x16x32_bf16 v[40:43], v[136:139], v[200:203], v[40:43]
	v_mfma_f32_16x16x32_bf16 v[32:35], v[144:147], v[200:203], v[32:35]
	s_setprio 2
	s_barrier
	v_mfma_f32_16x16x32_bf16 v[24:27], v[136:139], v[212:215], v[24:27]
	v_mfma_f32_16x16x32_bf16 v[16:19], v[144:147], v[212:215], v[16:19]
	s_setprio 0
	ds_read_b128 v[132:135], v248
	ds_read_b128 v[136:139], v248 offset:1024
	ds_read_b128 v[140:143], v248 offset:2048
	ds_read_b128 v[144:147], v248 offset:3072
	s_add_i32 s44, s44, s63
	v_lshl_add_u64 v[246:247], v[238:239], 0, s[84:85]
	s_mov_b32 m0, s44
	s_nop 0
	global_load_lds_dwordx4 v[246:247], off
	v_lshl_add_u64 v[246:247], v[240:241], 0, s[84:85]
	s_add_i32 m0, s44, 0x2000
	s_nop 0
	global_load_lds_dwordx4 v[246:247], off
	s_waitcnt vmcnt(6)
	s_barrier
	s_setprio 1
	v_mfma_f32_16x16x32_bf16 v[52:55], v[216:219], v[148:151], v[52:55]
	v_mfma_f32_16x16x32_bf16 v[44:47], v[224:227], v[148:151], v[44:47]
	v_mfma_f32_16x16x32_bf16 v[36:39], v[216:219], v[156:159], v[36:39]
	v_mfma_f32_16x16x32_bf16 v[28:31], v[224:227], v[156:159], v[28:31]
	v_mfma_f32_16x16x32_bf16 v[20:23], v[216:219], v[196:199], v[20:23]
	v_mfma_f32_16x16x32_bf16 v[12:15], v[224:227], v[196:199], v[12:15]
	v_mfma_f32_16x16x32_bf16 v[8:11], v[216:219], v[208:211], v[8:11]
	v_mfma_f32_16x16x32_bf16 v[4:7], v[224:227], v[208:211], v[4:7]
	v_mfma_f32_16x16x32_bf16 v[52:55], v[220:223], v[152:155], v[52:55]
	v_mfma_f32_16x16x32_bf16 v[44:47], v[228:231], v[152:155], v[44:47]
	v_mfma_f32_16x16x32_bf16 v[36:39], v[220:223], v[160:163], v[36:39]
	v_mfma_f32_16x16x32_bf16 v[28:31], v[228:231], v[160:163], v[28:31]
	v_mfma_f32_16x16x32_bf16 v[20:23], v[220:223], v[200:203], v[20:23]
	v_mfma_f32_16x16x32_bf16 v[12:15], v[228:231], v[200:203], v[12:15]
	s_setprio 2
	s_barrier
	v_mfma_f32_16x16x32_bf16 v[8:11], v[220:223], v[212:215], v[8:11]
	v_mfma_f32_16x16x32_bf16 v[4:7], v[228:231], v[212:215], v[4:7]
	s_setprio 0
	s_add_u32 s42, s42, 0x100
	s_addc_u32 s43, s43, 0
	s_add_u32 s58, s58, 0x100
	s_addc_u32 s59, s59, 0
	s_cmp_ge_u32 s78, s68
	s_mov_b32 s44, s78
	s_cbranch_scc0 .LBB0_514
	s_waitcnt lgkmcnt(0)
	v_lshl_or_b32 v190, s77, 8, v194
	v_ashrrev_i32_e32 v191, 31, v190
	v_cndmask_b32_e64 v132, 0, 1, s[36:37]
	v_cmp_ne_u32_e64 s[42:43], 1, v132
	s_andn2_b64 vcc, exec, s[36:37]
	v_lshl_add_u64 v[156:157], v[190:191], 2, s[48:49]
	s_cbranch_vccnz .LBB0_517
	global_load_dwordx4 v[132:135], v[156:157], off
	s_branch .LBB0_518
